# nt hint on the weight-transpose stores and the final LayerNorm output stores (streaming data never re-read soon)
# speedup vs baseline: 1.0019x; 1.0019x over previous
; __device__ __forceinline__ void transpose_item(const float* W, int K, int N, bf16* WT, int mode, LAS float* scr, int item, int lane) {
;     const int nblk = N / 32, kb = item / nblk, nb = item % nblk, k0 = 64 * kb, n0 = 32 * nb;
;     const int nsrc = colmap(mode, n0 + (lane & 31));
; #pragma unroll 8
;     for (int i = 0; i < 32; ++i) { const int kk = 2 * i + (lane >> 5); scr[kk * 33 + (lane & 31)] = W[(size_t)(k0 + kk) * N + nsrc]; }
; __device__ __forceinline__ void prologue(const Params& P, LAS unsigned char* lds, int tid_in) {
;     ...
;         { const int mat = r >> 3, sub = r & 7, nb = mat >> 1, which = mat & 1;
;           transpose_item(P.in[which ? I_WX : I_WA] + (size_t)(l * 8 + nb) * 128 * 128, 128, 128, (bf16*)(ws + WS_LW + l * SZ_LW) + (size_t)(nb * 256 + which * 128) * 128, 0, scr, sub, lane); }
.LBB0_28:
	s_lshl_b32 s53, s0, 1
	s_lshl_b32 s55, s52, 1
	v_or_b32_e32 v4, s55, v14
	s_add_i32 s58, s53, 4
	s_add_i32 s59, s55, 4
	v_mov_b32_e32 v23, v5
	s_add_i32 s61, s55, 8
	v_lshlrev_b64 v[66:67], 9, v[4:5]
	v_or_b32_e32 v22, s58, v3
	v_or_b32_e32 v4, s59, v14
	v_mov_b32_e32 v21, v5
	v_or_b32_e32 v20, s53, v3
	s_add_i32 s63, s55, 12
	v_lshlrev_b64 v[22:23], 9, v[22:23]
	v_lshlrev_b64 v[68:69], 9, v[4:5]
	v_or_b32_e32 v4, s61, v14
	s_add_i32 s60, s53, 8
	s_add_i32 s62, s53, 12
	s_add_i32 s65, s55, 16
	v_lshlrev_b64 v[20:21], 9, v[20:21]
	v_lshl_add_u64 v[66:67], v[12:13], 0, v[66:67]
	v_lshl_add_u64 v[22:23], v[12:13], 0, v[22:23]
	v_lshlrev_b64 v[70:71], 9, v[4:5]
	v_or_b32_e32 v4, s63, v14
	v_mov_b32_e32 v25, v5
	v_mov_b32_e32 v27, v5
	s_add_i32 s67, s55, 20
	v_or_b32_e32 v24, s60, v3
	v_or_b32_e32 v26, s62, v3
	v_lshl_add_u64 v[20:21], v[12:13], 0, v[20:21]
	v_lshl_add_u64 v[68:69], v[12:13], 0, v[68:69]
	global_load_dword v11, v[66:67], off
	global_load_dword v82, v[20:21], off
	global_load_dword v83, v[68:69], off
	global_load_dword v84, v[22:23], off
	v_lshlrev_b64 v[22:23], 9, v[4:5]
	v_or_b32_e32 v4, s65, v14
	s_add_i32 s64, s53, 16
	s_add_i32 s66, s53, 20
	s_add_i32 s69, s55, 24
	v_lshlrev_b64 v[24:25], 9, v[24:25]
	v_lshlrev_b64 v[26:27], 9, v[26:27]
	v_lshl_add_u64 v[20:21], v[12:13], 0, v[70:71]
	v_lshl_add_u64 v[22:23], v[12:13], 0, v[22:23]
	v_lshlrev_b64 v[66:67], 9, v[4:5]
	v_or_b32_e32 v4, s67, v14
	v_mov_b32_e32 v29, v5
	v_mov_b32_e32 v31, v5
	s_add_i32 s68, s53, 24
	s_add_i32 s70, s53, 28
	s_add_i32 s71, s55, 28
	v_or_b32_e32 v28, s64, v3
	v_or_b32_e32 v30, s66, v3
	v_lshl_add_u64 v[24:25], v[12:13], 0, v[24:25]
	v_lshl_add_u64 v[26:27], v[12:13], 0, v[26:27]
	global_load_dword v85, v[20:21], off
	global_load_dword v86, v[24:25], off
	global_load_dword v87, v[22:23], off
	global_load_dword v88, v[26:27], off
	v_lshlrev_b64 v[22:23], 9, v[4:5]
	v_or_b32_e32 v4, s69, v14
	v_mov_b32_e32 v35, v5
	v_mov_b32_e32 v37, v5
	v_or_b32_e32 v34, s68, v3
	v_or_b32_e32 v36, s70, v3
	v_lshlrev_b64 v[28:29], 9, v[28:29]
	v_lshlrev_b64 v[30:31], 9, v[30:31]
	v_lshl_add_u64 v[20:21], v[12:13], 0, v[66:67]
	v_lshl_add_u64 v[22:23], v[12:13], 0, v[22:23]
	v_lshlrev_b64 v[24:25], 9, v[4:5]
	v_or_b32_e32 v4, s71, v14
	v_lshlrev_b64 v[34:35], 9, v[34:35]
	v_lshlrev_b64 v[36:37], 9, v[36:37]
	v_lshl_add_u64 v[28:29], v[12:13], 0, v[28:29]
	v_lshl_add_u64 v[30:31], v[12:13], 0, v[30:31]
	global_load_dword v89, v[20:21], off
	global_load_dword v90, v[28:29], off
	global_load_dword v91, v[22:23], off
	global_load_dword v92, v[30:31], off
	v_lshl_add_u64 v[20:21], v[12:13], 0, v[24:25]
	v_lshlrev_b64 v[22:23], 9, v[4:5]
	v_lshl_add_u64 v[34:35], v[12:13], 0, v[34:35]
	v_lshl_add_u64 v[36:37], v[12:13], 0, v[36:37]
	v_lshl_add_u64 v[22:23], v[12:13], 0, v[22:23]
	global_load_dword v4, v[20:21], off
	global_load_dword v93, v[34:35], off
	global_load_dword v94, v[22:23], off
	global_load_dword v95, v[36:37], off
	v_or_b32_e32 v22, s53, v1
	v_or_b32_e32 v20, s55, v0
	s_add_i32 s52, s52, 16
	s_add_i32 s0, s0, 16
	s_add_i32 s1, s1, -16
	v_mad_u64_u32 v[20:21], s[56:57], v20, s46, v[2:3]
	v_mad_u64_u32 v[22:23], s[56:57], v22, s46, v[2:3]
	v_or_b32_e32 v21, s58, v1
	v_or_b32_e32 v23, s59, v0
	v_or_b32_e32 v30, s60, v1
	v_or_b32_e32 v28, s61, v0
	v_or_b32_e32 v36, s62, v1
	v_or_b32_e32 v34, s63, v0
	v_or_b32_e32 v68, s64, v1
	v_or_b32_e32 v66, s65, v0
	v_or_b32_e32 v72, s66, v1
	v_or_b32_e32 v70, s67, v0
	v_or_b32_e32 v76, s68, v1
	v_or_b32_e32 v74, s69, v0
	v_or_b32_e32 v80, s70, v1
	v_or_b32_e32 v78, s71, v0
	s_cmp_lg_u32 s1, 0
	v_mad_u64_u32 v[24:25], s[56:57], v23, s46, v[2:3]
	v_mad_u64_u32 v[26:27], s[56:57], v21, s46, v[2:3]
	v_mad_u64_u32 v[28:29], s[56:57], v28, s46, v[2:3]
	v_mad_u64_u32 v[30:31], s[56:57], v30, s46, v[2:3]
	v_mad_u64_u32 v[34:35], s[56:57], v34, s46, v[2:3]
	v_mad_u64_u32 v[36:37], s[56:57], v36, s46, v[2:3]
	v_mad_u64_u32 v[66:67], s[56:57], v66, s46, v[2:3]
	v_mad_u64_u32 v[68:69], s[56:57], v68, s46, v[2:3]
	v_mad_u64_u32 v[70:71], s[56:57], v70, s46, v[2:3]
	v_mad_u64_u32 v[72:73], s[56:57], v72, s46, v[2:3]
	v_mad_u64_u32 v[74:75], s[56:57], v74, s46, v[2:3]
	v_mad_u64_u32 v[76:77], s[56:57], v76, s46, v[2:3]
	v_mad_u64_u32 v[78:79], s[56:57], v78, s46, v[2:3]
	v_mad_u64_u32 v[80:81], s[56:57], v80, s46, v[2:3]
	s_waitcnt vmcnt(15)
	ds_write_b32 v20, v11
	s_waitcnt vmcnt(14)
	ds_write_b32 v22, v82
	s_waitcnt vmcnt(13)
	ds_write_b32 v24, v83
	s_waitcnt vmcnt(12)
	ds_write_b32 v26, v84
	s_waitcnt vmcnt(11)
	ds_write_b32 v28, v85
	s_waitcnt vmcnt(10)
	ds_write_b32 v30, v86
	s_waitcnt vmcnt(9)
	ds_write_b32 v34, v87
	s_waitcnt vmcnt(8)
	ds_write_b32 v36, v88
	s_waitcnt vmcnt(7)
	ds_write_b32 v66, v89
	s_waitcnt vmcnt(6)
	ds_write_b32 v68, v90
	s_waitcnt vmcnt(5)
	ds_write_b32 v70, v91
	s_waitcnt vmcnt(4)
	ds_write_b32 v72, v92
	s_waitcnt vmcnt(3)
	ds_write_b32 v74, v4
	s_waitcnt vmcnt(2)
	ds_write_b32 v76, v93
	s_waitcnt vmcnt(1)
	ds_write_b32 v78, v94
	s_waitcnt vmcnt(0)
	ds_write_b32 v80, v95
	s_cbranch_scc1 .LBB0_28
; #define LAS __attribute__((address_space(3)))
; __device__ __forceinline__ unsigned cvtpk(float lo, float hi) { f32x2_t v = {lo, hi}; bf16x2_t b = __builtin_convertvector(v, bf16x2_t); return __builtin_bit_cast(unsigned, b); }
; #define LDS_WAIT() asm volatile("s_waitcnt lgkmcnt(0)" ::: "memory")
; __device__ __forceinline__ void transpose_item(const float* W, int K, int N, bf16* WT, int mode, LAS float* scr, int item, int lane) {
;     ...
;     const int c = lane & 7;
; #pragma unroll
;     for (int j = 0; j < 4; ++j) { const int n = (lane >> 3) + 8 * j; const LAS float* s = scr + (8 * c) * 33 + n;
;         u32x4 o; o.x = cvtpk(s[0 * 33], s[1 * 33]); o.y = cvtpk(s[2 * 33], s[3 * 33]); o.z = cvtpk(s[4 * 33], s[5 * 33]); o.w = cvtpk(s[6 * 33], s[7 * 33]);
;         *(u32x4*)(WT + (size_t)(n0 + n) * K + k0 + 8 * c) = o; }
;     LDS_WAIT();
	v_lshlrev_b32_e32 v3, 7, v18
	v_ashrrev_i32_e32 v11, 31, v10
	v_lshl_or_b32 v4, v9, 8, v3
	s_waitcnt lgkmcnt(0)
	v_lshlrev_b64 v[10:11], 19, v[10:11]
	v_lshlrev_b64 v[12:13], 8, v[4:5]
	v_lshlrev_b32_e32 v4, 1, v19
	ds_read2_b32 v[18:19], v33 offset0:33 offset1:41
	ds_read2_b32 v[20:21], v33 offset1:8
	ds_read2_b32 v[22:23], v33 offset0:66 offset1:74
	ds_read2_b32 v[24:25], v33 offset0:99 offset1:107
	ds_read2_b32 v[26:27], v33 offset0:132 offset1:140
	ds_read2_b32 v[28:29], v33 offset0:165 offset1:173
	ds_read2_b32 v[30:31], v33 offset0:198 offset1:206
	ds_read2_b32 v[34:35], v33 offset0:231 offset1:239
	v_lshl_add_u64 v[10:11], s[4:5], 0, v[10:11]
	v_lshl_add_u64 v[10:11], v[10:11], 0, v[12:13]
	v_lshl_add_u64 v[10:11], v[10:11], 0, v[4:5]
	v_mov_b32_e32 v9, v5
	v_or_b32_e32 v3, v15, v17
	v_lshl_add_u64 v[36:37], v[10:11], 0, v[8:9]
	v_lshlrev_b32_e32 v4, 8, v3
	s_waitcnt lgkmcnt(6)
	v_cvt_pk_bf16_f32 v10, v20, v18
	s_waitcnt lgkmcnt(4)
	v_cvt_pk_bf16_f32 v11, v22, v24
	s_waitcnt lgkmcnt(2)
	v_cvt_pk_bf16_f32 v12, v26, v28
	s_waitcnt lgkmcnt(0)
	v_cvt_pk_bf16_f32 v13, v30, v34
	v_lshl_add_u64 v[66:67], v[36:37], 0, v[4:5]
	global_store_dwordx4 v[66:67], v[10:13], off nt
	v_or_b32_e32 v3, v15, v38
	v_lshlrev_b32_e32 v4, 8, v3
	v_cvt_pk_bf16_f32 v10, v21, v19
	v_cvt_pk_bf16_f32 v11, v23, v25
	v_cvt_pk_bf16_f32 v12, v27, v29
	v_cvt_pk_bf16_f32 v13, v31, v35
	ds_read2_b32 v[20:21], v33 offset0:49 offset1:57
	ds_read2_b32 v[22:23], v33 offset0:16 offset1:24
	ds_read2_b32 v[24:25], v33 offset0:82 offset1:90
	ds_read2_b32 v[26:27], v33 offset0:115 offset1:123
	ds_read2_b32 v[28:29], v33 offset0:148 offset1:156
	ds_read2_b32 v[30:31], v33 offset0:181 offset1:189
	ds_read2_b32 v[34:35], v33 offset0:214 offset1:222
	ds_read2_b32 v[66:67], v33 offset0:247 offset1:255
	v_or_b32_e32 v3, v15, v39
	v_lshl_add_u64 v[18:19], v[36:37], 0, v[4:5]
	v_lshlrev_b32_e32 v4, 8, v3
	v_or_b32_e32 v3, v15, v40
	global_store_dwordx4 v[18:19], v[10:13], off nt
	v_lshl_add_u64 v[18:19], v[36:37], 0, v[4:5]
	v_lshlrev_b32_e32 v4, 8, v3
	s_waitcnt lgkmcnt(6)
	v_cvt_pk_bf16_f32 v10, v22, v20
	s_waitcnt lgkmcnt(4)
	v_cvt_pk_bf16_f32 v11, v24, v26
	s_waitcnt lgkmcnt(2)
	v_cvt_pk_bf16_f32 v12, v28, v30
	s_waitcnt lgkmcnt(0)
	v_cvt_pk_bf16_f32 v13, v34, v66
	global_store_dwordx4 v[18:19], v[10:13], off nt
	v_lshl_add_u64 v[14:15], v[36:37], 0, v[4:5]
	s_nop 0
	v_cvt_pk_bf16_f32 v10, v23, v21
	v_cvt_pk_bf16_f32 v11, v25, v27
	v_cvt_pk_bf16_f32 v12, v29, v31
	v_cvt_pk_bf16_f32 v13, v35, v67
	global_store_dwordx4 v[14:15], v[10:13], off nt
	s_waitcnt lgkmcnt(0)

; __device__ __forceinline__ void transpose_item(const float* W, int K, int N, bf16* WT, int mode, LAS float* scr, int item, int lane) {
;     const int nblk = N / 32, kb = item / nblk, nb = item % nblk, k0 = 64 * kb, n0 = 32 * nb;
;     const int nsrc = colmap(mode, n0 + (lane & 31));
; #pragma unroll 8
;     for (int i = 0; i < 32; ++i) { const int kk = 2 * i + (lane >> 5); scr[kk * 33 + (lane & 31)] = W[(size_t)(k0 + kk) * N + nsrc]; }
; __device__ __forceinline__ void prologue(const Params& P, LAS unsigned char* lds, int tid_in) {
;     ...
;         if (r < IT_FO) { transpose_item(P.in[I_WFO] + (size_t)l * DFF * D, DFF, D, (bf16*)(ws + WS_WFO + l * SZ_WFO), 0, scr, r, lane); continue; } r -= IT_FO;
.LBB0_32:
	s_lshl_b32 s53, s44, 1
	s_lshl_b32 s55, s45, 1
	v_or_b32_e32 v4, s55, v14
	s_add_i32 s58, s53, 4
	s_add_i32 s59, s55, 4
	v_mov_b32_e32 v21, v5
	s_add_i32 s61, s55, 8
	v_lshlrev_b64 v[36:37], 12, v[4:5]
	v_or_b32_e32 v20, s58, v3
	v_or_b32_e32 v4, s59, v14
	v_mov_b32_e32 v19, v5
	v_or_b32_e32 v18, s53, v3
	s_add_i32 s63, s55, 12
	v_lshlrev_b64 v[20:21], 12, v[20:21]
	v_lshlrev_b64 v[66:67], 12, v[4:5]
	v_or_b32_e32 v4, s61, v14
	s_add_i32 s60, s53, 8
	s_add_i32 s62, s53, 12
	s_add_i32 s65, s55, 16
	v_lshlrev_b64 v[18:19], 12, v[18:19]
	v_lshl_add_u64 v[36:37], v[12:13], 0, v[36:37]
	v_lshl_add_u64 v[20:21], v[12:13], 0, v[20:21]
	v_lshlrev_b64 v[68:69], 12, v[4:5]
	v_or_b32_e32 v4, s63, v14
	v_mov_b32_e32 v23, v5
	v_mov_b32_e32 v25, v5
	s_add_i32 s67, s55, 20
	v_or_b32_e32 v22, s60, v3
	v_or_b32_e32 v24, s62, v3
	v_lshl_add_u64 v[18:19], v[12:13], 0, v[18:19]
	v_lshl_add_u64 v[66:67], v[12:13], 0, v[66:67]
	global_load_dword v15, v[36:37], off
	global_load_dword v80, v[18:19], off
	global_load_dword v81, v[66:67], off
	global_load_dword v82, v[20:21], off
	v_lshlrev_b64 v[20:21], 12, v[4:5]
	v_or_b32_e32 v4, s65, v14
	s_add_i32 s64, s53, 16
	s_add_i32 s66, s53, 20
	s_add_i32 s69, s55, 24
	v_lshlrev_b64 v[22:23], 12, v[22:23]
	v_lshlrev_b64 v[24:25], 12, v[24:25]
	v_lshl_add_u64 v[18:19], v[12:13], 0, v[68:69]
	v_lshl_add_u64 v[20:21], v[12:13], 0, v[20:21]
	v_lshlrev_b64 v[36:37], 12, v[4:5]
	v_or_b32_e32 v4, s67, v14
	v_mov_b32_e32 v27, v5
	v_mov_b32_e32 v29, v5
	s_add_i32 s68, s53, 24
	s_add_i32 s70, s53, 28
	s_add_i32 s71, s55, 28
	v_or_b32_e32 v26, s64, v3
	v_or_b32_e32 v28, s66, v3
	v_lshl_add_u64 v[22:23], v[12:13], 0, v[22:23]
	v_lshl_add_u64 v[24:25], v[12:13], 0, v[24:25]
	global_load_dword v83, v[18:19], off
	global_load_dword v84, v[22:23], off
	global_load_dword v85, v[20:21], off
	global_load_dword v86, v[24:25], off
	v_lshlrev_b64 v[20:21], 12, v[4:5]
	v_or_b32_e32 v4, s69, v14
	v_mov_b32_e32 v31, v5
	v_mov_b32_e32 v35, v5
	v_or_b32_e32 v30, s68, v3
	v_or_b32_e32 v34, s70, v3
	v_lshlrev_b64 v[26:27], 12, v[26:27]
	v_lshlrev_b64 v[28:29], 12, v[28:29]
	v_lshl_add_u64 v[18:19], v[12:13], 0, v[36:37]
	v_lshl_add_u64 v[20:21], v[12:13], 0, v[20:21]
	v_lshlrev_b64 v[22:23], 12, v[4:5]
	v_or_b32_e32 v4, s71, v14
	v_lshlrev_b64 v[30:31], 12, v[30:31]
	v_lshlrev_b64 v[34:35], 12, v[34:35]
	v_lshl_add_u64 v[26:27], v[12:13], 0, v[26:27]
	v_lshl_add_u64 v[28:29], v[12:13], 0, v[28:29]
	global_load_dword v87, v[18:19], off
	global_load_dword v88, v[26:27], off
	global_load_dword v89, v[20:21], off
	global_load_dword v90, v[28:29], off
	v_lshl_add_u64 v[18:19], v[12:13], 0, v[22:23]
	v_lshlrev_b64 v[20:21], 12, v[4:5]
	v_lshl_add_u64 v[30:31], v[12:13], 0, v[30:31]
	v_lshl_add_u64 v[34:35], v[12:13], 0, v[34:35]
	v_lshl_add_u64 v[20:21], v[12:13], 0, v[20:21]
	global_load_dword v4, v[18:19], off
	global_load_dword v91, v[30:31], off
	global_load_dword v92, v[20:21], off
	global_load_dword v93, v[34:35], off
	v_or_b32_e32 v20, s53, v1
	v_or_b32_e32 v18, s55, v0
	s_add_i32 s45, s45, 16
	s_add_i32 s44, s44, 16
	s_add_i32 s52, s52, -16
	v_mad_u64_u32 v[18:19], s[56:57], v18, s46, v[2:3]
	v_mad_u64_u32 v[20:21], s[56:57], v20, s46, v[2:3]
	v_or_b32_e32 v19, s58, v1
	v_or_b32_e32 v21, s59, v0
	v_or_b32_e32 v28, s60, v1
	v_or_b32_e32 v26, s61, v0
	v_or_b32_e32 v34, s62, v1
	v_or_b32_e32 v30, s63, v0
	v_or_b32_e32 v66, s64, v1
	v_or_b32_e32 v36, s65, v0
	v_or_b32_e32 v70, s66, v1
	v_or_b32_e32 v68, s67, v0
	v_or_b32_e32 v74, s68, v1
	v_or_b32_e32 v72, s69, v0
	v_or_b32_e32 v78, s70, v1
	v_or_b32_e32 v76, s71, v0
	s_cmp_lg_u32 s52, 0
	v_mad_u64_u32 v[22:23], s[56:57], v21, s46, v[2:3]
	v_mad_u64_u32 v[24:25], s[56:57], v19, s46, v[2:3]
	v_mad_u64_u32 v[26:27], s[56:57], v26, s46, v[2:3]
	v_mad_u64_u32 v[28:29], s[56:57], v28, s46, v[2:3]
	v_mad_u64_u32 v[30:31], s[56:57], v30, s46, v[2:3]
	v_mad_u64_u32 v[34:35], s[56:57], v34, s46, v[2:3]
	v_mad_u64_u32 v[36:37], s[56:57], v36, s46, v[2:3]
	v_mad_u64_u32 v[66:67], s[56:57], v66, s46, v[2:3]
	v_mad_u64_u32 v[68:69], s[56:57], v68, s46, v[2:3]
	v_mad_u64_u32 v[70:71], s[56:57], v70, s46, v[2:3]
	v_mad_u64_u32 v[72:73], s[56:57], v72, s46, v[2:3]
	v_mad_u64_u32 v[74:75], s[56:57], v74, s46, v[2:3]
	v_mad_u64_u32 v[76:77], s[56:57], v76, s46, v[2:3]
	v_mad_u64_u32 v[78:79], s[56:57], v78, s46, v[2:3]
	s_waitcnt vmcnt(15)
	ds_write_b32 v18, v15
	s_waitcnt vmcnt(14)
	ds_write_b32 v20, v80
	s_waitcnt vmcnt(13)
	ds_write_b32 v22, v81
	s_waitcnt vmcnt(12)
	ds_write_b32 v24, v82
	s_waitcnt vmcnt(11)
	ds_write_b32 v26, v83
	s_waitcnt vmcnt(10)
	ds_write_b32 v28, v84
	s_waitcnt vmcnt(9)
	ds_write_b32 v30, v85
	s_waitcnt vmcnt(8)
	ds_write_b32 v34, v86
	s_waitcnt vmcnt(7)
	ds_write_b32 v36, v87
	s_waitcnt vmcnt(6)
	ds_write_b32 v66, v88
	s_waitcnt vmcnt(5)
	ds_write_b32 v68, v89
	s_waitcnt vmcnt(4)
	ds_write_b32 v70, v90
	s_waitcnt vmcnt(3)
	ds_write_b32 v72, v4
	s_waitcnt vmcnt(2)
	ds_write_b32 v74, v91
	s_waitcnt vmcnt(1)
	ds_write_b32 v76, v92
	s_waitcnt vmcnt(0)
	ds_write_b32 v78, v93
	s_cbranch_scc1 .LBB0_32
; #define LAS __attribute__((address_space(3)))
; __device__ __forceinline__ unsigned cvtpk(float lo, float hi) { f32x2_t v = {lo, hi}; bf16x2_t b = __builtin_convertvector(v, bf16x2_t); return __builtin_bit_cast(unsigned, b); }
; #define LDS_WAIT() asm volatile("s_waitcnt lgkmcnt(0)" ::: "memory")
; __device__ __forceinline__ void transpose_item(const float* W, int K, int N, bf16* WT, int mode, LAS float* scr, int item, int lane) {
;     ...
;     const int c = lane & 7;
; #pragma unroll
;     for (int j = 0; j < 4; ++j) { const int n = (lane >> 3) + 8 * j; const LAS float* s = scr + (8 * c) * 33 + n;
;         u32x4 o; o.x = cvtpk(s[0 * 33], s[1 * 33]); o.y = cvtpk(s[2 * 33], s[3 * 33]); o.z = cvtpk(s[4 * 33], s[5 * 33]); o.w = cvtpk(s[6 * 33], s[7 * 33]);
;         *(u32x4*)(WT + (size_t)(n0 + n) * K + k0 + 8 * c) = o; }
;     LDS_WAIT();
	s_waitcnt lgkmcnt(0)
	ds_read2_b32 v[18:19], v33 offset0:33 offset1:41
	ds_read2_b32 v[20:21], v33 offset1:8
	ds_read2_b32 v[22:23], v33 offset0:66 offset1:74
	ds_read2_b32 v[24:25], v33 offset0:99 offset1:107
	ds_read2_b32 v[26:27], v33 offset0:132 offset1:140
	ds_read2_b32 v[28:29], v33 offset0:165 offset1:173
	ds_read2_b32 v[30:31], v33 offset0:198 offset1:206
	ds_read2_b32 v[34:35], v33 offset0:231 offset1:239
	v_mul_hi_i32_i24_e32 v13, 0x580000, v10
	v_mul_i32_i24_e32 v12, 0x580000, v10
	v_lshl_add_u64 v[12:13], s[8:9], 0, v[12:13]
	v_lshlrev_b32_e32 v4, 1, v9
	v_or_b32_e32 v3, v11, v17
	v_lshl_add_u64 v[12:13], v[12:13], 0, v[4:5]
	v_mov_b32_e32 v9, v5
	v_mul_u32_u24_e32 v3, 0xb00, v3
	v_lshl_add_u64 v[36:37], v[12:13], 0, v[8:9]
	v_lshlrev_b32_e32 v4, 1, v3
	s_waitcnt lgkmcnt(6)
	v_cvt_pk_bf16_f32 v12, v20, v18
	s_waitcnt lgkmcnt(4)
	v_cvt_pk_bf16_f32 v13, v22, v24
	s_waitcnt lgkmcnt(2)
	v_cvt_pk_bf16_f32 v14, v26, v28
	s_waitcnt lgkmcnt(0)
	v_cvt_pk_bf16_f32 v15, v30, v34
	v_lshl_add_u64 v[66:67], v[36:37], 0, v[4:5]
	global_store_dwordx4 v[66:67], v[12:15], off nt
	v_or_b32_e32 v3, v11, v38
	v_mul_u32_u24_e32 v3, 0xb00, v3
	v_cvt_pk_bf16_f32 v12, v21, v19
	v_cvt_pk_bf16_f32 v13, v23, v25
	v_cvt_pk_bf16_f32 v14, v27, v29
	v_cvt_pk_bf16_f32 v15, v31, v35
	ds_read2_b32 v[20:21], v33 offset0:16 offset1:24
	ds_read2_b32 v[22:23], v33 offset0:49 offset1:57
	ds_read2_b32 v[24:25], v33 offset0:82 offset1:90
	ds_read2_b32 v[26:27], v33 offset0:115 offset1:123
	ds_read2_b32 v[28:29], v33 offset0:148 offset1:156
	ds_read2_b32 v[30:31], v33 offset0:181 offset1:189
	ds_read2_b32 v[34:35], v33 offset0:214 offset1:222
	ds_read2_b32 v[66:67], v33 offset0:247 offset1:255
	v_lshlrev_b32_e32 v4, 1, v3
	v_or_b32_e32 v3, v11, v39
	v_mul_u32_u24_e32 v3, 0xb00, v3
	v_lshl_add_u64 v[18:19], v[36:37], 0, v[4:5]
	v_lshlrev_b32_e32 v4, 1, v3
	v_or_b32_e32 v3, v11, v40
	v_mul_u32_u24_e32 v3, 0xb00, v3
	global_store_dwordx4 v[18:19], v[12:15], off nt
	v_lshl_add_u64 v[18:19], v[36:37], 0, v[4:5]
	v_lshlrev_b32_e32 v4, 1, v3
	s_waitcnt lgkmcnt(6)
	v_cvt_pk_bf16_f32 v12, v20, v22
	s_waitcnt lgkmcnt(4)
	v_cvt_pk_bf16_f32 v13, v24, v26
	s_waitcnt lgkmcnt(2)
	v_cvt_pk_bf16_f32 v14, v28, v30
	s_waitcnt lgkmcnt(0)
	v_cvt_pk_bf16_f32 v15, v34, v66
	global_store_dwordx4 v[18:19], v[12:15], off nt
	v_lshl_add_u64 v[10:11], v[36:37], 0, v[4:5]
	s_nop 0
	v_cvt_pk_bf16_f32 v12, v21, v23
	v_cvt_pk_bf16_f32 v13, v25, v27
	v_cvt_pk_bf16_f32 v14, v29, v31
	v_cvt_pk_bf16_f32 v15, v35, v67
	global_store_dwordx4 v[10:11], v[12:15], off nt
	s_waitcnt lgkmcnt(0)

; #define LAS __attribute__((address_space(3)))
; __device__ __forceinline__ unsigned cvtpk(float lo, float hi) { f32x2_t v = {lo, hi}; bf16x2_t b = __builtin_convertvector(v, bf16x2_t); return __builtin_bit_cast(unsigned, b); }
; #define LDS_WAIT() asm volatile("s_waitcnt lgkmcnt(0)" ::: "memory")
; __device__ __forceinline__ void transpose_item(const float* W, int K, int N, bf16* WT, int mode, LAS float* scr, int item, int lane) {
;     ...
;     const int c = lane & 7;
; #pragma unroll
;     for (int j = 0; j < 4; ++j) { const int n = (lane >> 3) + 8 * j; const LAS float* s = scr + (8 * c) * 33 + n;
;         u32x4 o; o.x = cvtpk(s[0 * 33], s[1 * 33]); o.y = cvtpk(s[2 * 33], s[3 * 33]); o.z = cvtpk(s[4 * 33], s[5 * 33]); o.w = cvtpk(s[6 * 33], s[7 * 33]);
;         *(u32x4*)(WT + (size_t)(n0 + n) * K + k0 + 8 * c) = o; }
;     LDS_WAIT();
.LBB0_40:
	s_or_b64 exec, exec, s[0:1]
	s_waitcnt lgkmcnt(0)
	ds_read2_b32 v[18:19], v33 offset0:33 offset1:41
	ds_read2_b32 v[20:21], v33 offset1:8
	ds_read2_b32 v[22:23], v33 offset0:66 offset1:74
	ds_read2_b32 v[24:25], v33 offset0:99 offset1:107
	ds_read2_b32 v[26:27], v33 offset0:132 offset1:140
	ds_read2_b32 v[28:29], v33 offset0:165 offset1:173
	ds_read2_b32 v[30:31], v33 offset0:198 offset1:206
	ds_read2_b32 v[34:35], v33 offset0:231 offset1:239
	v_mov_b64_e32 v[12:13], s[10:11]
	v_mad_i64_i32 v[12:13], s[0:1], v10, s47, v[12:13]
	v_lshlrev_b32_e32 v4, 1, v3
	v_lshl_add_u64 v[12:13], v[12:13], 0, v[4:5]
	v_mov_b32_e32 v9, v5
	v_or_b32_e32 v3, v11, v17
	v_lshl_add_u64 v[36:37], v[12:13], 0, v[8:9]
	v_lshlrev_b32_e32 v4, 11, v3
	s_waitcnt lgkmcnt(6)
	v_cvt_pk_bf16_f32 v12, v20, v18
	s_waitcnt lgkmcnt(4)
	v_cvt_pk_bf16_f32 v13, v22, v24
	s_waitcnt lgkmcnt(2)
	v_cvt_pk_bf16_f32 v14, v26, v28
	s_waitcnt lgkmcnt(0)
	v_cvt_pk_bf16_f32 v15, v30, v34
	v_lshl_add_u64 v[66:67], v[36:37], 0, v[4:5]
	global_store_dwordx4 v[66:67], v[12:15], off nt
	v_or_b32_e32 v3, v11, v38
	v_lshlrev_b32_e32 v4, 11, v3
	v_cvt_pk_bf16_f32 v12, v21, v19
	v_cvt_pk_bf16_f32 v13, v23, v25
	v_cvt_pk_bf16_f32 v14, v27, v29
	v_cvt_pk_bf16_f32 v15, v31, v35
	ds_read2_b32 v[20:21], v33 offset0:49 offset1:57
	ds_read2_b32 v[22:23], v33 offset0:16 offset1:24
	ds_read2_b32 v[24:25], v33 offset0:82 offset1:90
	ds_read2_b32 v[26:27], v33 offset0:115 offset1:123
	ds_read2_b32 v[28:29], v33 offset0:148 offset1:156
	ds_read2_b32 v[30:31], v33 offset0:181 offset1:189
	ds_read2_b32 v[34:35], v33 offset0:214 offset1:222
	ds_read2_b32 v[66:67], v33 offset0:247 offset1:255
	v_or_b32_e32 v3, v11, v39
	v_lshl_add_u64 v[18:19], v[36:37], 0, v[4:5]
	v_lshlrev_b32_e32 v4, 11, v3
	v_or_b32_e32 v3, v11, v40
	global_store_dwordx4 v[18:19], v[12:15], off nt
	v_lshl_add_u64 v[18:19], v[36:37], 0, v[4:5]
	v_lshlrev_b32_e32 v4, 11, v3
	s_waitcnt lgkmcnt(6)
	v_cvt_pk_bf16_f32 v12, v22, v20
	s_waitcnt lgkmcnt(4)
	v_cvt_pk_bf16_f32 v13, v24, v26
	s_waitcnt lgkmcnt(2)
	v_cvt_pk_bf16_f32 v14, v28, v30
	s_waitcnt lgkmcnt(0)
	v_cvt_pk_bf16_f32 v15, v34, v66
	global_store_dwordx4 v[18:19], v[12:15], off nt
	v_lshl_add_u64 v[10:11], v[36:37], 0, v[4:5]
	s_nop 0
	v_cvt_pk_bf16_f32 v12, v23, v21
	v_cvt_pk_bf16_f32 v13, v25, v27
	v_cvt_pk_bf16_f32 v14, v29, v31
	v_cvt_pk_bf16_f32 v15, v35, v67
	global_store_dwordx4 v[10:11], v[12:15], off nt
	s_waitcnt lgkmcnt(0)

; __device__ __forceinline__ void transpose_item(const float* W, int K, int N, bf16* WT, int mode, LAS float* scr, int item, int lane) {
;     const int nblk = N / 32, kb = item / nblk, nb = item % nblk, k0 = 64 * kb, n0 = 32 * nb;
;     const int nsrc = colmap(mode, n0 + (lane & 31));
; #pragma unroll 8
;     for (int i = 0; i < 32; ++i) { const int kk = 2 * i + (lane >> 5); scr[kk * 33 + (lane & 31)] = W[(size_t)(k0 + kk) * N + nsrc]; }
.LBB0_44:
	s_lshl_b32 s43, s40, 1
	s_lshl_b32 s44, s41, 1
	v_or_b32_e32 v4, s44, v14
	s_add_i32 s52, s43, 4
	s_add_i32 s53, s44, 4
	v_mov_b32_e32 v21, v5
	s_add_i32 s56, s44, 8
	v_lshlrev_b64 v[36:37], 12, v[4:5]
	v_or_b32_e32 v20, s52, v3
	v_or_b32_e32 v4, s53, v14
	v_mov_b32_e32 v19, v5
	v_or_b32_e32 v18, s43, v3
	s_add_i32 s58, s44, 12
	v_lshlrev_b64 v[20:21], 12, v[20:21]
	v_lshlrev_b64 v[66:67], 12, v[4:5]
	v_or_b32_e32 v4, s56, v14
	s_add_i32 s55, s43, 8
	s_add_i32 s57, s43, 12
	s_add_i32 s60, s44, 16
	v_lshlrev_b64 v[18:19], 12, v[18:19]
	v_lshl_add_u64 v[36:37], v[12:13], 0, v[36:37]
	v_lshl_add_u64 v[20:21], v[12:13], 0, v[20:21]
	v_lshlrev_b64 v[68:69], 12, v[4:5]
	v_or_b32_e32 v4, s58, v14
	v_mov_b32_e32 v23, v5
	v_mov_b32_e32 v25, v5
	s_add_i32 s62, s44, 20
	v_or_b32_e32 v22, s55, v3
	v_or_b32_e32 v24, s57, v3
	v_lshl_add_u64 v[18:19], v[12:13], 0, v[18:19]
	v_lshl_add_u64 v[66:67], v[12:13], 0, v[66:67]
	global_load_dword v80, v[36:37], off
	global_load_dword v81, v[18:19], off
	global_load_dword v82, v[66:67], off
	global_load_dword v83, v[20:21], off
	v_lshlrev_b64 v[20:21], 12, v[4:5]
	v_or_b32_e32 v4, s60, v14
	s_add_i32 s59, s43, 16
	s_add_i32 s61, s43, 20
	s_add_i32 s64, s44, 24
	v_lshlrev_b64 v[22:23], 12, v[22:23]
	v_lshlrev_b64 v[24:25], 12, v[24:25]
	v_lshl_add_u64 v[18:19], v[12:13], 0, v[68:69]
	v_lshl_add_u64 v[20:21], v[12:13], 0, v[20:21]
	v_lshlrev_b64 v[36:37], 12, v[4:5]
	v_or_b32_e32 v4, s62, v14
	v_mov_b32_e32 v27, v5
	v_mov_b32_e32 v29, v5
	s_add_i32 s63, s43, 24
	s_add_i32 s65, s43, 28
	s_add_i32 s66, s44, 28
	v_or_b32_e32 v26, s59, v3
	v_or_b32_e32 v28, s61, v3
	v_lshl_add_u64 v[22:23], v[12:13], 0, v[22:23]
	v_lshl_add_u64 v[24:25], v[12:13], 0, v[24:25]
	global_load_dword v84, v[18:19], off
	global_load_dword v85, v[22:23], off
	global_load_dword v86, v[20:21], off
	global_load_dword v87, v[24:25], off
	v_lshlrev_b64 v[20:21], 12, v[4:5]
	v_or_b32_e32 v4, s64, v14
	v_mov_b32_e32 v31, v5
	v_mov_b32_e32 v35, v5
	v_or_b32_e32 v30, s63, v3
	v_or_b32_e32 v34, s65, v3
	v_lshlrev_b64 v[26:27], 12, v[26:27]
	v_lshlrev_b64 v[28:29], 12, v[28:29]
	v_lshl_add_u64 v[18:19], v[12:13], 0, v[36:37]
	v_lshl_add_u64 v[20:21], v[12:13], 0, v[20:21]
	v_lshlrev_b64 v[22:23], 12, v[4:5]
	v_or_b32_e32 v4, s66, v14
	v_lshlrev_b64 v[30:31], 12, v[30:31]
	v_lshlrev_b64 v[34:35], 12, v[34:35]
	v_lshl_add_u64 v[26:27], v[12:13], 0, v[26:27]
	v_lshl_add_u64 v[28:29], v[12:13], 0, v[28:29]
	global_load_dword v88, v[18:19], off
	global_load_dword v89, v[26:27], off
	global_load_dword v90, v[20:21], off
	global_load_dword v91, v[28:29], off
	v_lshl_add_u64 v[18:19], v[12:13], 0, v[22:23]
	v_lshlrev_b64 v[20:21], 12, v[4:5]
	v_lshl_add_u64 v[30:31], v[12:13], 0, v[30:31]
	v_lshl_add_u64 v[34:35], v[12:13], 0, v[34:35]
	v_lshl_add_u64 v[20:21], v[12:13], 0, v[20:21]
	global_load_dword v4, v[18:19], off
	global_load_dword v92, v[30:31], off
	global_load_dword v93, v[20:21], off
	global_load_dword v94, v[34:35], off
	v_or_b32_e32 v20, s43, v1
	v_or_b32_e32 v18, s44, v0
	s_add_i32 s41, s41, 16
	s_add_i32 s40, s40, 16
	s_add_i32 s42, s42, -16
	v_mad_u64_u32 v[18:19], s[44:45], v18, s46, v[2:3]
	v_mad_u64_u32 v[20:21], s[44:45], v20, s46, v[2:3]
	v_or_b32_e32 v19, s52, v1
	v_or_b32_e32 v21, s53, v0
	v_or_b32_e32 v28, s55, v1
	v_or_b32_e32 v26, s56, v0
	v_or_b32_e32 v34, s57, v1
	v_or_b32_e32 v30, s58, v0
	v_or_b32_e32 v66, s59, v1
	v_or_b32_e32 v36, s60, v0
	v_or_b32_e32 v70, s61, v1
	v_or_b32_e32 v68, s62, v0
	v_or_b32_e32 v74, s63, v1
	v_or_b32_e32 v72, s64, v0
	v_or_b32_e32 v78, s65, v1
	v_or_b32_e32 v76, s66, v0
	s_cmp_lg_u32 s42, 0
	v_mad_u64_u32 v[22:23], s[44:45], v21, s46, v[2:3]
	v_mad_u64_u32 v[24:25], s[44:45], v19, s46, v[2:3]
	v_mad_u64_u32 v[26:27], s[44:45], v26, s46, v[2:3]
	v_mad_u64_u32 v[28:29], s[44:45], v28, s46, v[2:3]
	v_mad_u64_u32 v[30:31], s[44:45], v30, s46, v[2:3]
	v_mad_u64_u32 v[34:35], s[44:45], v34, s46, v[2:3]
	v_mad_u64_u32 v[36:37], s[44:45], v36, s46, v[2:3]
	v_mad_u64_u32 v[66:67], s[44:45], v66, s46, v[2:3]
	v_mad_u64_u32 v[68:69], s[44:45], v68, s46, v[2:3]
	v_mad_u64_u32 v[70:71], s[44:45], v70, s46, v[2:3]
	v_mad_u64_u32 v[72:73], s[44:45], v72, s46, v[2:3]
	v_mad_u64_u32 v[74:75], s[44:45], v74, s46, v[2:3]
	v_mad_u64_u32 v[76:77], s[44:45], v76, s46, v[2:3]
	v_mad_u64_u32 v[78:79], s[44:45], v78, s46, v[2:3]
	s_waitcnt vmcnt(15)
	ds_write_b32 v18, v80
	s_waitcnt vmcnt(14)
	ds_write_b32 v20, v81
	s_waitcnt vmcnt(13)
	ds_write_b32 v22, v82
	s_waitcnt vmcnt(12)
	ds_write_b32 v24, v83
	s_waitcnt vmcnt(11)
	ds_write_b32 v26, v84
	s_waitcnt vmcnt(10)
	ds_write_b32 v28, v85
	s_waitcnt vmcnt(9)
	ds_write_b32 v30, v86
	s_waitcnt vmcnt(8)
	ds_write_b32 v34, v87
	s_waitcnt vmcnt(7)
	ds_write_b32 v36, v88
	s_waitcnt vmcnt(6)
	ds_write_b32 v66, v89
	s_waitcnt vmcnt(5)
	ds_write_b32 v68, v90
	s_waitcnt vmcnt(4)
	ds_write_b32 v70, v91
	s_waitcnt vmcnt(3)
	ds_write_b32 v72, v4
	s_waitcnt vmcnt(2)
	ds_write_b32 v74, v92
	s_waitcnt vmcnt(1)
	ds_write_b32 v76, v93
	s_waitcnt vmcnt(0)
	ds_write_b32 v78, v94
	s_cbranch_scc1 .LBB0_44
; #define LAS __attribute__((address_space(3)))
; __device__ __forceinline__ unsigned cvtpk(float lo, float hi) { f32x2_t v = {lo, hi}; bf16x2_t b = __builtin_convertvector(v, bf16x2_t); return __builtin_bit_cast(unsigned, b); }
; #define LDS_WAIT() asm volatile("s_waitcnt lgkmcnt(0)" ::: "memory")
; __device__ __forceinline__ void transpose_item(const float* W, int K, int N, bf16* WT, int mode, LAS float* scr, int item, int lane) {
;     ...
;     const int c = lane & 7;
; #pragma unroll
;     for (int j = 0; j < 4; ++j) { const int n = (lane >> 3) + 8 * j; const LAS float* s = scr + (8 * c) * 33 + n;
;         u32x4 o; o.x = cvtpk(s[0 * 33], s[1 * 33]); o.y = cvtpk(s[2 * 33], s[3 * 33]); o.z = cvtpk(s[4 * 33], s[5 * 33]); o.w = cvtpk(s[6 * 33], s[7 * 33]);
;         *(u32x4*)(WT + (size_t)(n0 + n) * K + k0 + 8 * c) = o; }
;     LDS_WAIT();
	s_waitcnt lgkmcnt(0)
	ds_read2_b32 v[18:19], v33 offset0:33 offset1:41
	ds_read2_b32 v[20:21], v33 offset1:8
	ds_read2_b32 v[22:23], v33 offset0:66 offset1:74
	ds_read2_b32 v[24:25], v33 offset0:99 offset1:107
	ds_read2_b32 v[26:27], v33 offset0:132 offset1:140
	ds_read2_b32 v[28:29], v33 offset0:165 offset1:173
	ds_read2_b32 v[30:31], v33 offset0:198 offset1:206
	ds_read2_b32 v[34:35], v33 offset0:231 offset1:239
	v_lshlrev_b64 v[10:11], 21, v[10:11]
	v_lshl_add_u64 v[10:11], s[14:15], 0, v[10:11]
	v_lshlrev_b32_e32 v4, 1, v9
	v_lshl_add_u64 v[10:11], v[10:11], 0, v[4:5]
	v_mov_b32_e32 v9, v5
	v_or_b32_e32 v3, v15, v17
	v_lshl_add_u64 v[36:37], v[10:11], 0, v[8:9]
	v_lshlrev_b32_e32 v4, 11, v3
	s_waitcnt lgkmcnt(6)
	v_cvt_pk_bf16_f32 v10, v20, v18
	s_waitcnt lgkmcnt(4)
	v_cvt_pk_bf16_f32 v11, v22, v24
	s_waitcnt lgkmcnt(2)
	v_cvt_pk_bf16_f32 v12, v26, v28
	s_waitcnt lgkmcnt(0)
	v_cvt_pk_bf16_f32 v13, v30, v34
	v_lshl_add_u64 v[66:67], v[36:37], 0, v[4:5]
	global_store_dwordx4 v[66:67], v[10:13], off nt
	v_or_b32_e32 v3, v15, v38
	v_lshlrev_b32_e32 v4, 11, v3
	v_cvt_pk_bf16_f32 v10, v21, v19
	v_cvt_pk_bf16_f32 v11, v23, v25
	v_cvt_pk_bf16_f32 v12, v27, v29
	v_cvt_pk_bf16_f32 v13, v31, v35
	ds_read2_b32 v[20:21], v33 offset0:49 offset1:57
	ds_read2_b32 v[22:23], v33 offset0:16 offset1:24
	ds_read2_b32 v[24:25], v33 offset0:82 offset1:90
	ds_read2_b32 v[26:27], v33 offset0:115 offset1:123
	ds_read2_b32 v[28:29], v33 offset0:148 offset1:156
	ds_read2_b32 v[30:31], v33 offset0:181 offset1:189
	ds_read2_b32 v[34:35], v33 offset0:214 offset1:222
	ds_read2_b32 v[66:67], v33 offset0:247 offset1:255
	v_or_b32_e32 v3, v15, v39
	v_lshl_add_u64 v[18:19], v[36:37], 0, v[4:5]
	v_lshlrev_b32_e32 v4, 11, v3
	v_or_b32_e32 v3, v15, v40
	global_store_dwordx4 v[18:19], v[10:13], off nt
	v_lshl_add_u64 v[18:19], v[36:37], 0, v[4:5]
	v_lshlrev_b32_e32 v4, 11, v3
	s_waitcnt lgkmcnt(6)
	v_cvt_pk_bf16_f32 v10, v22, v20
	s_waitcnt lgkmcnt(4)
	v_cvt_pk_bf16_f32 v11, v24, v26
	s_waitcnt lgkmcnt(2)
	v_cvt_pk_bf16_f32 v12, v28, v30
	s_waitcnt lgkmcnt(0)
	v_cvt_pk_bf16_f32 v13, v34, v66
	global_store_dwordx4 v[18:19], v[10:13], off nt
	v_lshl_add_u64 v[14:15], v[36:37], 0, v[4:5]
	s_nop 0
	v_cvt_pk_bf16_f32 v10, v23, v21
	v_cvt_pk_bf16_f32 v11, v25, v27
	v_cvt_pk_bf16_f32 v12, v29, v31
	v_cvt_pk_bf16_f32 v13, v35, v67
	global_store_dwordx4 v[14:15], v[10:13], off nt
	s_waitcnt lgkmcnt(0)

; __device__ __forceinline__ void transpose_item(const float* W, int K, int N, bf16* WT, int mode, LAS float* scr, int item, int lane) {
;     const int nblk = N / 32, kb = item / nblk, nb = item % nblk, k0 = 64 * kb, n0 = 32 * nb;
;     const int nsrc = colmap(mode, n0 + (lane & 31));
; #pragma unroll 8
;     for (int i = 0; i < 32; ++i) { const int kk = 2 * i + (lane >> 5); scr[kk * 33 + (lane & 31)] = W[(size_t)(k0 + kk) * N + nsrc]; }
.LBB0_49:
	s_lshl_b32 s41, s38, 1
	s_lshl_b32 s42, s39, 1
	v_or_b32_e32 v4, s42, v14
	s_add_i32 s44, s41, 4
	s_add_i32 s45, s42, 4
	v_mov_b32_e32 v21, v5
	s_add_i32 s53, s42, 8
	v_lshlrev_b64 v[36:37], 12, v[4:5]
	v_or_b32_e32 v20, s44, v3
	v_or_b32_e32 v4, s45, v14
	v_mov_b32_e32 v19, v5
	v_or_b32_e32 v18, s41, v3
	s_add_i32 s56, s42, 12
	v_lshlrev_b64 v[20:21], 12, v[20:21]
	v_lshlrev_b64 v[66:67], 12, v[4:5]
	v_or_b32_e32 v4, s53, v14
	s_add_i32 s52, s41, 8
	s_add_i32 s55, s41, 12
	s_add_i32 s58, s42, 16
	v_lshlrev_b64 v[18:19], 12, v[18:19]
	v_lshl_add_u64 v[36:37], v[12:13], 0, v[36:37]
	v_lshl_add_u64 v[20:21], v[12:13], 0, v[20:21]
	v_lshlrev_b64 v[68:69], 12, v[4:5]
	v_or_b32_e32 v4, s56, v14
	v_mov_b32_e32 v23, v5
	v_mov_b32_e32 v25, v5
	s_add_i32 s60, s42, 20
	v_or_b32_e32 v22, s52, v3
	v_or_b32_e32 v24, s55, v3
	v_lshl_add_u64 v[18:19], v[12:13], 0, v[18:19]
	v_lshl_add_u64 v[66:67], v[12:13], 0, v[66:67]
	global_load_dword v80, v[36:37], off
	global_load_dword v81, v[18:19], off
	global_load_dword v82, v[66:67], off
	global_load_dword v83, v[20:21], off
	v_lshlrev_b64 v[20:21], 12, v[4:5]
	v_or_b32_e32 v4, s58, v14
	s_add_i32 s57, s41, 16
	s_add_i32 s59, s41, 20
	s_add_i32 s62, s42, 24
	v_lshlrev_b64 v[22:23], 12, v[22:23]
	v_lshlrev_b64 v[24:25], 12, v[24:25]
	v_lshl_add_u64 v[18:19], v[12:13], 0, v[68:69]
	v_lshl_add_u64 v[20:21], v[12:13], 0, v[20:21]
	v_lshlrev_b64 v[36:37], 12, v[4:5]
	v_or_b32_e32 v4, s60, v14
	v_mov_b32_e32 v27, v5
	v_mov_b32_e32 v29, v5
	s_add_i32 s61, s41, 24
	s_add_i32 s63, s41, 28
	s_add_i32 s64, s42, 28
	v_or_b32_e32 v26, s57, v3
	v_or_b32_e32 v28, s59, v3
	v_lshl_add_u64 v[22:23], v[12:13], 0, v[22:23]
	v_lshl_add_u64 v[24:25], v[12:13], 0, v[24:25]
	global_load_dword v84, v[18:19], off
	global_load_dword v85, v[22:23], off
	global_load_dword v86, v[20:21], off
	global_load_dword v87, v[24:25], off
	v_lshlrev_b64 v[20:21], 12, v[4:5]
	v_or_b32_e32 v4, s62, v14
	v_mov_b32_e32 v31, v5
	v_mov_b32_e32 v35, v5
	v_or_b32_e32 v30, s61, v3
	v_or_b32_e32 v34, s63, v3
	v_lshlrev_b64 v[26:27], 12, v[26:27]
	v_lshlrev_b64 v[28:29], 12, v[28:29]
	v_lshl_add_u64 v[18:19], v[12:13], 0, v[36:37]
	v_lshl_add_u64 v[20:21], v[12:13], 0, v[20:21]
	v_lshlrev_b64 v[22:23], 12, v[4:5]
	v_or_b32_e32 v4, s64, v14
	v_lshlrev_b64 v[30:31], 12, v[30:31]
	v_lshlrev_b64 v[34:35], 12, v[34:35]
	v_lshl_add_u64 v[26:27], v[12:13], 0, v[26:27]
	v_lshl_add_u64 v[28:29], v[12:13], 0, v[28:29]
	global_load_dword v88, v[18:19], off
	global_load_dword v89, v[26:27], off
	global_load_dword v90, v[20:21], off
	global_load_dword v91, v[28:29], off
	v_lshl_add_u64 v[18:19], v[12:13], 0, v[22:23]
	v_lshlrev_b64 v[20:21], 12, v[4:5]
	v_lshl_add_u64 v[30:31], v[12:13], 0, v[30:31]
	v_lshl_add_u64 v[34:35], v[12:13], 0, v[34:35]
	v_lshl_add_u64 v[20:21], v[12:13], 0, v[20:21]
	global_load_dword v4, v[18:19], off
	global_load_dword v92, v[30:31], off
	global_load_dword v93, v[20:21], off
	global_load_dword v94, v[34:35], off
	v_or_b32_e32 v20, s41, v1
	v_or_b32_e32 v18, s42, v0
	s_add_i32 s39, s39, 16
	s_add_i32 s38, s38, 16
	s_add_i32 s40, s40, -16
	v_mad_u64_u32 v[18:19], s[42:43], v18, s46, v[2:3]
	v_mad_u64_u32 v[20:21], s[42:43], v20, s46, v[2:3]
	v_or_b32_e32 v19, s44, v1
	v_or_b32_e32 v21, s45, v0
	v_or_b32_e32 v28, s52, v1
	v_or_b32_e32 v26, s53, v0
	v_or_b32_e32 v34, s55, v1
	v_or_b32_e32 v30, s56, v0
	v_or_b32_e32 v66, s57, v1
	v_or_b32_e32 v36, s58, v0
	v_or_b32_e32 v70, s59, v1
	v_or_b32_e32 v68, s60, v0
	v_or_b32_e32 v74, s61, v1
	v_or_b32_e32 v72, s62, v0
	v_or_b32_e32 v78, s63, v1
	v_or_b32_e32 v76, s64, v0
	s_cmp_lg_u32 s40, 0
	v_mad_u64_u32 v[22:23], s[42:43], v21, s46, v[2:3]
	v_mad_u64_u32 v[24:25], s[42:43], v19, s46, v[2:3]
	v_mad_u64_u32 v[26:27], s[42:43], v26, s46, v[2:3]
	v_mad_u64_u32 v[28:29], s[42:43], v28, s46, v[2:3]
	v_mad_u64_u32 v[30:31], s[42:43], v30, s46, v[2:3]
	v_mad_u64_u32 v[34:35], s[42:43], v34, s46, v[2:3]
	v_mad_u64_u32 v[36:37], s[42:43], v36, s46, v[2:3]
	v_mad_u64_u32 v[66:67], s[42:43], v66, s46, v[2:3]
	v_mad_u64_u32 v[68:69], s[42:43], v68, s46, v[2:3]
	v_mad_u64_u32 v[70:71], s[42:43], v70, s46, v[2:3]
	v_mad_u64_u32 v[72:73], s[42:43], v72, s46, v[2:3]
	v_mad_u64_u32 v[74:75], s[42:43], v74, s46, v[2:3]
	v_mad_u64_u32 v[76:77], s[42:43], v76, s46, v[2:3]
	v_mad_u64_u32 v[78:79], s[42:43], v78, s46, v[2:3]
	s_waitcnt vmcnt(15)
	ds_write_b32 v18, v80
	s_waitcnt vmcnt(14)
	ds_write_b32 v20, v81
	s_waitcnt vmcnt(13)
	ds_write_b32 v22, v82
	s_waitcnt vmcnt(12)
	ds_write_b32 v24, v83
	s_waitcnt vmcnt(11)
	ds_write_b32 v26, v84
	s_waitcnt vmcnt(10)
	ds_write_b32 v28, v85
	s_waitcnt vmcnt(9)
	ds_write_b32 v30, v86
	s_waitcnt vmcnt(8)
	ds_write_b32 v34, v87
	s_waitcnt vmcnt(7)
	ds_write_b32 v36, v88
	s_waitcnt vmcnt(6)
	ds_write_b32 v66, v89
	s_waitcnt vmcnt(5)
	ds_write_b32 v68, v90
	s_waitcnt vmcnt(4)
	ds_write_b32 v70, v91
	s_waitcnt vmcnt(3)
	ds_write_b32 v72, v4
	s_waitcnt vmcnt(2)
	ds_write_b32 v74, v92
	s_waitcnt vmcnt(1)
	ds_write_b32 v76, v93
	s_waitcnt vmcnt(0)
	ds_write_b32 v78, v94
	s_cbranch_scc1 .LBB0_49
; #define LAS __attribute__((address_space(3)))
; __device__ __forceinline__ unsigned cvtpk(float lo, float hi) { f32x2_t v = {lo, hi}; bf16x2_t b = __builtin_convertvector(v, bf16x2_t); return __builtin_bit_cast(unsigned, b); }
; #define LDS_WAIT() asm volatile("s_waitcnt lgkmcnt(0)" ::: "memory")
; __device__ __forceinline__ void transpose_item(const float* W, int K, int N, bf16* WT, int mode, LAS float* scr, int item, int lane) {
;     ...
;     const int c = lane & 7;
; #pragma unroll
;     for (int j = 0; j < 4; ++j) { const int n = (lane >> 3) + 8 * j; const LAS float* s = scr + (8 * c) * 33 + n;
;         u32x4 o; o.x = cvtpk(s[0 * 33], s[1 * 33]); o.y = cvtpk(s[2 * 33], s[3 * 33]); o.z = cvtpk(s[4 * 33], s[5 * 33]); o.w = cvtpk(s[6 * 33], s[7 * 33]);
;         *(u32x4*)(WT + (size_t)(n0 + n) * K + k0 + 8 * c) = o; }
;     LDS_WAIT();
	s_waitcnt lgkmcnt(0)
	ds_read2_b32 v[18:19], v33 offset0:33 offset1:41
	ds_read2_b32 v[20:21], v33 offset1:8
	ds_read2_b32 v[22:23], v33 offset0:66 offset1:74
	ds_read2_b32 v[24:25], v33 offset0:99 offset1:107
	ds_read2_b32 v[26:27], v33 offset0:132 offset1:140
	ds_read2_b32 v[28:29], v33 offset0:165 offset1:173
	ds_read2_b32 v[30:31], v33 offset0:198 offset1:206
	ds_read2_b32 v[34:35], v33 offset0:231 offset1:239
	v_lshlrev_b64 v[10:11], 21, v[10:11]
	v_lshl_add_u64 v[10:11], s[16:17], 0, v[10:11]
	v_lshlrev_b32_e32 v4, 1, v9
	v_lshl_add_u64 v[10:11], v[10:11], 0, v[4:5]
	v_mov_b32_e32 v9, v5
	v_or_b32_e32 v3, v15, v17
	v_lshl_add_u64 v[36:37], v[10:11], 0, v[8:9]
	v_lshlrev_b32_e32 v4, 11, v3
	s_waitcnt lgkmcnt(6)
	v_cvt_pk_bf16_f32 v10, v20, v18
	s_waitcnt lgkmcnt(4)
	v_cvt_pk_bf16_f32 v11, v22, v24
	s_waitcnt lgkmcnt(2)
	v_cvt_pk_bf16_f32 v12, v26, v28
	s_waitcnt lgkmcnt(0)
	v_cvt_pk_bf16_f32 v13, v30, v34
	v_lshl_add_u64 v[66:67], v[36:37], 0, v[4:5]
	global_store_dwordx4 v[66:67], v[10:13], off nt
	v_or_b32_e32 v3, v15, v38
	v_lshlrev_b32_e32 v4, 11, v3
	v_cvt_pk_bf16_f32 v10, v21, v19
	v_cvt_pk_bf16_f32 v11, v23, v25
	v_cvt_pk_bf16_f32 v12, v27, v29
	v_cvt_pk_bf16_f32 v13, v31, v35
	ds_read2_b32 v[20:21], v33 offset0:49 offset1:57
	ds_read2_b32 v[22:23], v33 offset0:16 offset1:24
	ds_read2_b32 v[24:25], v33 offset0:82 offset1:90
	ds_read2_b32 v[26:27], v33 offset0:115 offset1:123
	ds_read2_b32 v[28:29], v33 offset0:148 offset1:156
	ds_read2_b32 v[30:31], v33 offset0:181 offset1:189
	ds_read2_b32 v[34:35], v33 offset0:214 offset1:222
	ds_read2_b32 v[66:67], v33 offset0:247 offset1:255
	v_or_b32_e32 v3, v15, v39
	v_lshl_add_u64 v[18:19], v[36:37], 0, v[4:5]
	v_lshlrev_b32_e32 v4, 11, v3
	v_or_b32_e32 v3, v15, v40
	global_store_dwordx4 v[18:19], v[10:13], off nt
	v_lshl_add_u64 v[18:19], v[36:37], 0, v[4:5]
	v_lshlrev_b32_e32 v4, 11, v3
	s_waitcnt lgkmcnt(6)
	v_cvt_pk_bf16_f32 v10, v22, v20
	s_waitcnt lgkmcnt(4)
	v_cvt_pk_bf16_f32 v11, v24, v26
	s_waitcnt lgkmcnt(2)
	v_cvt_pk_bf16_f32 v12, v28, v30
	s_waitcnt lgkmcnt(0)
	v_cvt_pk_bf16_f32 v13, v34, v66
	global_store_dwordx4 v[18:19], v[10:13], off nt
	v_lshl_add_u64 v[14:15], v[36:37], 0, v[4:5]
	s_nop 0
	v_cvt_pk_bf16_f32 v10, v23, v21
	v_cvt_pk_bf16_f32 v11, v25, v27
	v_cvt_pk_bf16_f32 v12, v29, v31
	v_cvt_pk_bf16_f32 v13, v35, v67
	global_store_dwordx4 v[14:15], v[10:13], off nt
	s_waitcnt lgkmcnt(0)

; __device__ __forceinline__ void transpose_item(const float* W, int K, int N, bf16* WT, int mode, LAS float* scr, int item, int lane) {
;     const int nblk = N / 32, kb = item / nblk, nb = item % nblk, k0 = 64 * kb, n0 = 32 * nb;
;     const int nsrc = colmap(mode, n0 + (lane & 31));
; #pragma unroll 8
;     for (int i = 0; i < 32; ++i) { const int kk = 2 * i + (lane >> 5); scr[kk * 33 + (lane & 31)] = W[(size_t)(k0 + kk) * N + nsrc]; }
; __device__ __forceinline__ void prologue(const Params& P, LAS unsigned char* lds, int tid_in) {
;     ...
;         if (r < IT_AP) { transpose_item(P.in[I_WAP] + (size_t)l * 512 * D, 512, D, (bf16*)(ws + WS_WAP + l * SZ_WAP), 0, scr, r, lane); continue; } r -= IT_AP;
.LBB0_54:
	s_lshl_b32 s39, s36, 1
	s_lshl_b32 s40, s37, 1
	v_or_b32_e32 v4, s40, v14
	s_add_i32 s42, s39, 4
	s_add_i32 s43, s40, 4
	v_mov_b32_e32 v21, v5
	s_add_i32 s45, s40, 8
	v_lshlrev_b64 v[36:37], 12, v[4:5]
	v_or_b32_e32 v20, s42, v3
	v_or_b32_e32 v4, s43, v14
	v_mov_b32_e32 v19, v5
	v_or_b32_e32 v18, s39, v3
	s_add_i32 s53, s40, 12
	v_lshlrev_b64 v[20:21], 12, v[20:21]
	v_lshlrev_b64 v[66:67], 12, v[4:5]
	v_or_b32_e32 v4, s45, v14
	s_add_i32 s44, s39, 8
	s_add_i32 s52, s39, 12
	s_add_i32 s56, s40, 16
	v_lshlrev_b64 v[18:19], 12, v[18:19]
	v_lshl_add_u64 v[36:37], v[12:13], 0, v[36:37]
	v_lshl_add_u64 v[20:21], v[12:13], 0, v[20:21]
	v_lshlrev_b64 v[68:69], 12, v[4:5]
	v_or_b32_e32 v4, s53, v14
	v_mov_b32_e32 v23, v5
	v_mov_b32_e32 v25, v5
	s_add_i32 s58, s40, 20
	v_or_b32_e32 v22, s44, v3
	v_or_b32_e32 v24, s52, v3
	v_lshl_add_u64 v[18:19], v[12:13], 0, v[18:19]
	v_lshl_add_u64 v[66:67], v[12:13], 0, v[66:67]
	global_load_dword v80, v[36:37], off
	global_load_dword v81, v[18:19], off
	global_load_dword v82, v[66:67], off
	global_load_dword v83, v[20:21], off
	v_lshlrev_b64 v[20:21], 12, v[4:5]
	v_or_b32_e32 v4, s56, v14
	s_add_i32 s55, s39, 16
	s_add_i32 s57, s39, 20
	s_add_i32 s60, s40, 24
	v_lshlrev_b64 v[22:23], 12, v[22:23]
	v_lshlrev_b64 v[24:25], 12, v[24:25]
	v_lshl_add_u64 v[18:19], v[12:13], 0, v[68:69]
	v_lshl_add_u64 v[20:21], v[12:13], 0, v[20:21]
	v_lshlrev_b64 v[36:37], 12, v[4:5]
	v_or_b32_e32 v4, s58, v14
	v_mov_b32_e32 v27, v5
	v_mov_b32_e32 v29, v5
	s_add_i32 s59, s39, 24
	s_add_i32 s61, s39, 28
	s_add_i32 s62, s40, 28
	v_or_b32_e32 v26, s55, v3
	v_or_b32_e32 v28, s57, v3
	v_lshl_add_u64 v[22:23], v[12:13], 0, v[22:23]
	v_lshl_add_u64 v[24:25], v[12:13], 0, v[24:25]
	global_load_dword v84, v[18:19], off
	global_load_dword v85, v[22:23], off
	global_load_dword v86, v[20:21], off
	global_load_dword v87, v[24:25], off
	v_lshlrev_b64 v[20:21], 12, v[4:5]
	v_or_b32_e32 v4, s60, v14
	v_mov_b32_e32 v31, v5
	v_mov_b32_e32 v35, v5
	v_or_b32_e32 v30, s59, v3
	v_or_b32_e32 v34, s61, v3
	v_lshlrev_b64 v[26:27], 12, v[26:27]
	v_lshlrev_b64 v[28:29], 12, v[28:29]
	v_lshl_add_u64 v[18:19], v[12:13], 0, v[36:37]
	v_lshl_add_u64 v[20:21], v[12:13], 0, v[20:21]
	v_lshlrev_b64 v[22:23], 12, v[4:5]
	v_or_b32_e32 v4, s62, v14
	v_lshlrev_b64 v[30:31], 12, v[30:31]
	v_lshlrev_b64 v[34:35], 12, v[34:35]
	v_lshl_add_u64 v[26:27], v[12:13], 0, v[26:27]
	v_lshl_add_u64 v[28:29], v[12:13], 0, v[28:29]
	global_load_dword v88, v[18:19], off
	global_load_dword v89, v[26:27], off
	global_load_dword v90, v[20:21], off
	global_load_dword v91, v[28:29], off
	v_lshl_add_u64 v[18:19], v[12:13], 0, v[22:23]
	v_lshlrev_b64 v[20:21], 12, v[4:5]
	v_lshl_add_u64 v[30:31], v[12:13], 0, v[30:31]
	v_lshl_add_u64 v[34:35], v[12:13], 0, v[34:35]
	v_lshl_add_u64 v[20:21], v[12:13], 0, v[20:21]
	global_load_dword v4, v[18:19], off
	global_load_dword v92, v[30:31], off
	global_load_dword v93, v[20:21], off
	global_load_dword v94, v[34:35], off
	v_or_b32_e32 v20, s39, v1
	v_or_b32_e32 v18, s40, v0
	s_add_i32 s37, s37, 16
	s_add_i32 s36, s36, 16
	s_add_i32 s38, s38, -16
	v_mad_u64_u32 v[18:19], s[40:41], v18, s46, v[2:3]
	v_mad_u64_u32 v[20:21], s[40:41], v20, s46, v[2:3]
	v_or_b32_e32 v19, s42, v1
	v_or_b32_e32 v21, s43, v0
	v_or_b32_e32 v28, s44, v1
	v_or_b32_e32 v26, s45, v0
	v_or_b32_e32 v34, s52, v1
	v_or_b32_e32 v30, s53, v0
	v_or_b32_e32 v66, s55, v1
	v_or_b32_e32 v36, s56, v0
	v_or_b32_e32 v70, s57, v1
	v_or_b32_e32 v68, s58, v0
	v_or_b32_e32 v74, s59, v1
	v_or_b32_e32 v72, s60, v0
	v_or_b32_e32 v78, s61, v1
	v_or_b32_e32 v76, s62, v0
	s_cmp_lg_u32 s38, 0
	v_mad_u64_u32 v[22:23], s[40:41], v21, s46, v[2:3]
	v_mad_u64_u32 v[24:25], s[40:41], v19, s46, v[2:3]
	v_mad_u64_u32 v[26:27], s[40:41], v26, s46, v[2:3]
	v_mad_u64_u32 v[28:29], s[40:41], v28, s46, v[2:3]
	v_mad_u64_u32 v[30:31], s[40:41], v30, s46, v[2:3]
	v_mad_u64_u32 v[34:35], s[40:41], v34, s46, v[2:3]
	v_mad_u64_u32 v[36:37], s[40:41], v36, s46, v[2:3]
	v_mad_u64_u32 v[66:67], s[40:41], v66, s46, v[2:3]
	v_mad_u64_u32 v[68:69], s[40:41], v68, s46, v[2:3]
	v_mad_u64_u32 v[70:71], s[40:41], v70, s46, v[2:3]
	v_mad_u64_u32 v[72:73], s[40:41], v72, s46, v[2:3]
	v_mad_u64_u32 v[74:75], s[40:41], v74, s46, v[2:3]
	v_mad_u64_u32 v[76:77], s[40:41], v76, s46, v[2:3]
	v_mad_u64_u32 v[78:79], s[40:41], v78, s46, v[2:3]
	s_waitcnt vmcnt(15)
	ds_write_b32 v18, v80
	s_waitcnt vmcnt(14)
	ds_write_b32 v20, v81
	s_waitcnt vmcnt(13)
	ds_write_b32 v22, v82
	s_waitcnt vmcnt(12)
	ds_write_b32 v24, v83
	s_waitcnt vmcnt(11)
	ds_write_b32 v26, v84
	s_waitcnt vmcnt(10)
	ds_write_b32 v28, v85
	s_waitcnt vmcnt(9)
	ds_write_b32 v30, v86
	s_waitcnt vmcnt(8)
	ds_write_b32 v34, v87
	s_waitcnt vmcnt(7)
	ds_write_b32 v36, v88
	s_waitcnt vmcnt(6)
	ds_write_b32 v66, v89
	s_waitcnt vmcnt(5)
	ds_write_b32 v68, v90
	s_waitcnt vmcnt(4)
	ds_write_b32 v70, v91
	s_waitcnt vmcnt(3)
	ds_write_b32 v72, v4
	s_waitcnt vmcnt(2)
	ds_write_b32 v74, v92
	s_waitcnt vmcnt(1)
	ds_write_b32 v76, v93
	s_waitcnt vmcnt(0)
	ds_write_b32 v78, v94
	s_cbranch_scc1 .LBB0_54
; #define LAS __attribute__((address_space(3)))
; __device__ __forceinline__ unsigned cvtpk(float lo, float hi) { f32x2_t v = {lo, hi}; bf16x2_t b = __builtin_convertvector(v, bf16x2_t); return __builtin_bit_cast(unsigned, b); }
; #define LDS_WAIT() asm volatile("s_waitcnt lgkmcnt(0)" ::: "memory")
; __device__ __forceinline__ void transpose_item(const float* W, int K, int N, bf16* WT, int mode, LAS float* scr, int item, int lane) {
;     ...
;     const int c = lane & 7;
; #pragma unroll
;     for (int j = 0; j < 4; ++j) { const int n = (lane >> 3) + 8 * j; const LAS float* s = scr + (8 * c) * 33 + n;
;         u32x4 o; o.x = cvtpk(s[0 * 33], s[1 * 33]); o.y = cvtpk(s[2 * 33], s[3 * 33]); o.z = cvtpk(s[4 * 33], s[5 * 33]); o.w = cvtpk(s[6 * 33], s[7 * 33]);
;         *(u32x4*)(WT + (size_t)(n0 + n) * K + k0 + 8 * c) = o; }
;     LDS_WAIT();
	s_waitcnt lgkmcnt(0)
	ds_read2_b32 v[18:19], v33 offset0:33 offset1:41
	ds_read2_b32 v[20:21], v33 offset1:8
	ds_read2_b32 v[22:23], v33 offset0:66 offset1:74
	ds_read2_b32 v[24:25], v33 offset0:99 offset1:107
	ds_read2_b32 v[26:27], v33 offset0:132 offset1:140
	ds_read2_b32 v[28:29], v33 offset0:165 offset1:173
	ds_read2_b32 v[30:31], v33 offset0:198 offset1:206
	ds_read2_b32 v[34:35], v33 offset0:231 offset1:239
	v_lshlrev_b64 v[10:11], 20, v[10:11]
	v_lshl_add_u64 v[10:11], s[18:19], 0, v[10:11]
	v_lshlrev_b32_e32 v4, 1, v9
	v_lshl_add_u64 v[10:11], v[10:11], 0, v[4:5]
	v_mov_b32_e32 v9, v5
	v_or_b32_e32 v3, v15, v17
	v_lshl_add_u64 v[36:37], v[10:11], 0, v[8:9]
	v_lshlrev_b32_e32 v4, 10, v3
	s_waitcnt lgkmcnt(6)
	v_cvt_pk_bf16_f32 v10, v20, v18
	s_waitcnt lgkmcnt(4)
	v_cvt_pk_bf16_f32 v11, v22, v24
	s_waitcnt lgkmcnt(2)
	v_cvt_pk_bf16_f32 v12, v26, v28
	s_waitcnt lgkmcnt(0)
	v_cvt_pk_bf16_f32 v13, v30, v34
	v_lshl_add_u64 v[66:67], v[36:37], 0, v[4:5]
	global_store_dwordx4 v[66:67], v[10:13], off nt
	v_or_b32_e32 v3, v15, v38
	v_lshlrev_b32_e32 v4, 10, v3
	v_cvt_pk_bf16_f32 v10, v21, v19
	v_cvt_pk_bf16_f32 v11, v23, v25
	v_cvt_pk_bf16_f32 v12, v27, v29
	v_cvt_pk_bf16_f32 v13, v31, v35
	ds_read2_b32 v[20:21], v33 offset0:49 offset1:57
	ds_read2_b32 v[22:23], v33 offset0:16 offset1:24
	ds_read2_b32 v[24:25], v33 offset0:82 offset1:90
	ds_read2_b32 v[26:27], v33 offset0:115 offset1:123
	ds_read2_b32 v[28:29], v33 offset0:148 offset1:156
	ds_read2_b32 v[30:31], v33 offset0:181 offset1:189
	ds_read2_b32 v[34:35], v33 offset0:214 offset1:222
	ds_read2_b32 v[66:67], v33 offset0:247 offset1:255
	v_or_b32_e32 v3, v15, v39
	v_lshl_add_u64 v[18:19], v[36:37], 0, v[4:5]
	v_lshlrev_b32_e32 v4, 10, v3
	v_or_b32_e32 v3, v15, v40
	global_store_dwordx4 v[18:19], v[10:13], off nt
	v_lshl_add_u64 v[18:19], v[36:37], 0, v[4:5]
	v_lshlrev_b32_e32 v4, 10, v3
	s_waitcnt lgkmcnt(6)
	v_cvt_pk_bf16_f32 v10, v22, v20
	s_waitcnt lgkmcnt(4)
	v_cvt_pk_bf16_f32 v11, v24, v26
	s_waitcnt lgkmcnt(2)
	v_cvt_pk_bf16_f32 v12, v28, v30
	s_waitcnt lgkmcnt(0)
	v_cvt_pk_bf16_f32 v13, v34, v66
	global_store_dwordx4 v[18:19], v[10:13], off nt
	v_lshl_add_u64 v[14:15], v[36:37], 0, v[4:5]
	s_nop 0
	v_cvt_pk_bf16_f32 v10, v23, v21
	v_cvt_pk_bf16_f32 v11, v25, v27
	v_cvt_pk_bf16_f32 v12, v29, v31
	v_cvt_pk_bf16_f32 v13, v35, v67
	global_store_dwordx4 v[14:15], v[10:13], off nt
	s_waitcnt lgkmcnt(0)

; #define LAS __attribute__((address_space(3)))
; __device__ __forceinline__ unsigned cvtpk(float lo, float hi) { f32x2_t v = {lo, hi}; bf16x2_t b = __builtin_convertvector(v, bf16x2_t); return __builtin_bit_cast(unsigned, b); }
; #define LDS_WAIT() asm volatile("s_waitcnt lgkmcnt(0)" ::: "memory")
; __device__ __forceinline__ void transpose_item(const float* W, int K, int N, bf16* WT, int mode, LAS float* scr, int item, int lane) {
;     ...
;     const int c = lane & 7;
; #pragma unroll
;     for (int j = 0; j < 4; ++j) { const int n = (lane >> 3) + 8 * j; const LAS float* s = scr + (8 * c) * 33 + n;
;         u32x4 o; o.x = cvtpk(s[0 * 33], s[1 * 33]); o.y = cvtpk(s[2 * 33], s[3 * 33]); o.z = cvtpk(s[4 * 33], s[5 * 33]); o.w = cvtpk(s[6 * 33], s[7 * 33]);
;         *(u32x4*)(WT + (size_t)(n0 + n) * K + k0 + 8 * c) = o; }
;     LDS_WAIT();
.LBB0_63:
	s_or_b64 exec, exec, s[0:1]
	v_readlane_b32 s24, v252, 1
	v_readlane_b32 s28, v252, 5
	v_readlane_b32 s29, v252, 6
	s_mov_b32 s0, 0x980000
	s_waitcnt lgkmcnt(0)
	v_ashrrev_i32_e32 v13, 31, v12
	v_mov_b64_e32 v[18:19], s[28:29]
	v_mad_i64_i32 v[10:11], s[0:1], v10, s0, v[18:19]
	ds_read2_b32 v[18:19], v33 offset0:33 offset1:41
	s_waitcnt lgkmcnt(1)
	ds_read2_b32 v[20:21], v33 offset1:8
	ds_read2_b32 v[22:23], v33 offset0:66 offset1:74
	ds_read2_b32 v[24:25], v33 offset0:99 offset1:107
	ds_read2_b32 v[26:27], v33 offset0:132 offset1:140
	ds_read2_b32 v[28:29], v33 offset0:165 offset1:173
	ds_read2_b32 v[30:31], v33 offset0:198 offset1:206
	ds_read2_b32 v[34:35], v33 offset0:231 offset1:239
	v_or_b32_e32 v66, v14, v17
	v_lshl_add_u64 v[10:11], v[12:13], 1, v[10:11]
	v_mov_b32_e32 v9, v5
	v_ashrrev_i32_e32 v67, 31, v66
	v_lshl_add_u64 v[36:37], v[10:11], 0, v[8:9]
	v_lshlrev_b64 v[66:67], 11, v[66:67]
	s_waitcnt lgkmcnt(6)
	v_cvt_pk_bf16_f32 v10, v20, v18
	s_waitcnt lgkmcnt(4)
	v_cvt_pk_bf16_f32 v11, v22, v24
	s_waitcnt lgkmcnt(2)
	v_cvt_pk_bf16_f32 v12, v26, v28
	s_waitcnt lgkmcnt(0)
	v_cvt_pk_bf16_f32 v13, v30, v34
	v_lshl_add_u64 v[66:67], v[36:37], 0, v[66:67]
	v_or_b32_e32 v18, v14, v38
	global_store_dwordx4 v[66:67], v[10:13], off nt
	v_readlane_b32 s25, v252, 2
	v_readlane_b32 s26, v252, 3
	v_cvt_pk_bf16_f32 v10, v21, v19
	v_ashrrev_i32_e32 v19, 31, v18
	v_cvt_pk_bf16_f32 v11, v23, v25
	v_cvt_pk_bf16_f32 v12, v27, v29
	v_cvt_pk_bf16_f32 v13, v31, v35
	v_lshlrev_b64 v[18:19], 11, v[18:19]
	ds_read2_b32 v[20:21], v33 offset0:49 offset1:57
	ds_read2_b32 v[22:23], v33 offset0:16 offset1:24
	ds_read2_b32 v[24:25], v33 offset0:82 offset1:90
	ds_read2_b32 v[26:27], v33 offset0:115 offset1:123
	ds_read2_b32 v[28:29], v33 offset0:148 offset1:156
	ds_read2_b32 v[30:31], v33 offset0:181 offset1:189
	ds_read2_b32 v[34:35], v33 offset0:214 offset1:222
	ds_read2_b32 v[66:67], v33 offset0:247 offset1:255
	v_lshl_add_u64 v[18:19], v[36:37], 0, v[18:19]
	global_store_dwordx4 v[18:19], v[10:13], off nt
	v_or_b32_e32 v18, v14, v39
	v_ashrrev_i32_e32 v19, 31, v18
	v_or_b32_e32 v14, v14, v40
	v_lshlrev_b64 v[18:19], 11, v[18:19]
	v_ashrrev_i32_e32 v15, 31, v14
	s_waitcnt lgkmcnt(6)
	v_cvt_pk_bf16_f32 v10, v22, v20
	s_waitcnt lgkmcnt(4)
	v_cvt_pk_bf16_f32 v11, v24, v26
	s_waitcnt lgkmcnt(2)
	v_cvt_pk_bf16_f32 v12, v28, v30
	s_waitcnt lgkmcnt(0)
	v_cvt_pk_bf16_f32 v13, v34, v66
	v_lshl_add_u64 v[18:19], v[36:37], 0, v[18:19]
	v_lshlrev_b64 v[14:15], 11, v[14:15]
	global_store_dwordx4 v[18:19], v[10:13], off nt
	v_lshl_add_u64 v[14:15], v[36:37], 0, v[14:15]
	v_readlane_b32 s27, v252, 4
	v_cvt_pk_bf16_f32 v10, v23, v21
	v_cvt_pk_bf16_f32 v11, v25, v27
	v_cvt_pk_bf16_f32 v12, v29, v31
	v_cvt_pk_bf16_f32 v13, v35, v67
	global_store_dwordx4 v[14:15], v[10:13], off nt
	s_waitcnt lgkmcnt(0)
	v_readlane_b32 s30, v252, 7
	v_readlane_b32 s31, v252, 8

; #define LAS __attribute__((address_space(3)))
; __device__ __forceinline__ unsigned cvtpk(float lo, float hi) { f32x2_t v = {lo, hi}; bf16x2_t b = __builtin_convertvector(v, bf16x2_t); return __builtin_bit_cast(unsigned, b); }
; #define LDS_WAIT() asm volatile("s_waitcnt lgkmcnt(0)" ::: "memory")
; __device__ __forceinline__ void transpose_item(const float* W, int K, int N, bf16* WT, int mode, LAS float* scr, int item, int lane) {
;     const int nblk = N / 32, kb = item / nblk, nb = item % nblk, k0 = 64 * kb, n0 = 32 * nb;
;     const int nsrc = colmap(mode, n0 + (lane & 31));
; #pragma unroll 8
;     for (int i = 0; i < 32; ++i) { const int kk = 2 * i + (lane >> 5); scr[kk * 33 + (lane & 31)] = W[(size_t)(k0 + kk) * N + nsrc]; }
;     LDS_WAIT();
;     const int c = lane & 7;
; #pragma unroll
;     for (int j = 0; j < 4; ++j) { const int n = (lane >> 3) + 8 * j; const LAS float* s = scr + (8 * c) * 33 + n;
;         u32x4 o; o.x = cvtpk(s[0 * 33], s[1 * 33]); o.y = cvtpk(s[2 * 33], s[3 * 33]); o.z = cvtpk(s[4 * 33], s[5 * 33]); o.w = cvtpk(s[6 * 33], s[7 * 33]);
;         *(u32x4*)(WT + (size_t)(n0 + n) * K + k0 + 8 * c) = o; }
;     LDS_WAIT();
.LBB0_66:
	s_lshl_b32 s39, s0, 1
	s_lshl_b32 s42, s1, 1
	v_or_b32_e32 v11, s39, v3
	v_or_b32_e32 v14, s42, v4
	s_add_i32 s43, s39, 4
	s_add_i32 s44, s42, 4
	s_add_i32 s45, s39, 8
	s_add_i32 s52, s42, 8
	s_add_i32 s53, s39, 12
	s_add_i32 s55, s42, 12
	s_add_i32 s56, s39, 16
	s_add_i32 s57, s42, 16
	s_add_i32 s58, s39, 20
	s_add_i32 s59, s42, 20
	s_add_i32 s60, s39, 24
	s_add_i32 s61, s42, 24
	s_add_i32 s62, s39, 28
	s_add_i32 s63, s42, 28
	v_mad_i64_i32 v[14:15], s[40:41], v14, s50, v[12:13]
	v_mad_i64_i32 v[18:19], s[40:41], v11, s50, v[12:13]
	v_or_b32_e32 v11, s43, v3
	v_or_b32_e32 v20, s44, v4
	v_or_b32_e32 v26, s45, v3
	v_or_b32_e32 v24, s52, v4
	v_or_b32_e32 v30, s53, v3
	v_or_b32_e32 v28, s55, v4
	v_or_b32_e32 v36, s56, v3
	v_or_b32_e32 v34, s57, v4
	v_or_b32_e32 v68, s58, v3
	v_or_b32_e32 v66, s59, v4
	v_or_b32_e32 v72, s60, v3
	v_or_b32_e32 v70, s61, v4
	v_or_b32_e32 v76, s62, v3
	v_or_b32_e32 v74, s63, v4
	v_mad_i64_i32 v[20:21], s[40:41], v20, s50, v[12:13]
	v_mad_i64_i32 v[22:23], s[40:41], v11, s50, v[12:13]
	v_mad_i64_i32 v[24:25], s[40:41], v24, s50, v[12:13]
	v_mad_i64_i32 v[26:27], s[40:41], v26, s50, v[12:13]
	v_mad_i64_i32 v[28:29], s[40:41], v28, s50, v[12:13]
	v_mad_i64_i32 v[30:31], s[40:41], v30, s50, v[12:13]
	v_mad_i64_i32 v[34:35], s[40:41], v34, s50, v[12:13]
	v_mad_i64_i32 v[36:37], s[40:41], v36, s50, v[12:13]
	v_mad_i64_i32 v[66:67], s[40:41], v66, s50, v[12:13]
	v_mad_i64_i32 v[68:69], s[40:41], v68, s50, v[12:13]
	v_mad_i64_i32 v[70:71], s[40:41], v70, s50, v[12:13]
	v_mad_i64_i32 v[72:73], s[40:41], v72, s50, v[12:13]
	v_mad_i64_i32 v[74:75], s[40:41], v74, s50, v[12:13]
	v_mad_i64_i32 v[76:77], s[40:41], v76, s50, v[12:13]
	global_load_dword v11, v[14:15], off
	global_load_dword v78, v[18:19], off
	global_load_dword v79, v[20:21], off
	global_load_dword v80, v[22:23], off
	global_load_dword v81, v[24:25], off
	global_load_dword v82, v[26:27], off
	global_load_dword v83, v[28:29], off
	global_load_dword v84, v[30:31], off
	global_load_dword v85, v[34:35], off
	global_load_dword v86, v[36:37], off
	global_load_dword v87, v[66:67], off
	global_load_dword v88, v[68:69], off
	global_load_dword v89, v[70:71], off
	global_load_dword v90, v[72:73], off
	global_load_dword v91, v[74:75], off
	global_load_dword v92, v[76:77], off
	v_or_b32_e32 v18, s39, v1
	v_or_b32_e32 v14, s42, v0
	s_add_i32 s1, s1, 16
	s_add_i32 s0, s0, 16
	s_add_i32 s38, s38, -16
	v_mad_u64_u32 v[14:15], s[40:41], v14, s46, v[2:3]
	v_mad_u64_u32 v[18:19], s[40:41], v18, s46, v[2:3]
	v_or_b32_e32 v15, s43, v1
	v_or_b32_e32 v19, s44, v0
	v_or_b32_e32 v26, s45, v1
	v_or_b32_e32 v24, s52, v0
	v_or_b32_e32 v30, s53, v1
	v_or_b32_e32 v28, s55, v0
	v_or_b32_e32 v36, s56, v1
	v_or_b32_e32 v34, s57, v0
	v_or_b32_e32 v68, s58, v1
	v_or_b32_e32 v66, s59, v0
	v_or_b32_e32 v72, s60, v1
	v_or_b32_e32 v70, s61, v0
	v_or_b32_e32 v76, s62, v1
	v_or_b32_e32 v74, s63, v0
	s_cmp_lg_u32 s38, 0
	v_mad_u64_u32 v[20:21], s[40:41], v19, s46, v[2:3]
	v_mad_u64_u32 v[22:23], s[40:41], v15, s46, v[2:3]
	v_mad_u64_u32 v[24:25], s[40:41], v24, s46, v[2:3]
	v_mad_u64_u32 v[26:27], s[40:41], v26, s46, v[2:3]
	v_mad_u64_u32 v[28:29], s[40:41], v28, s46, v[2:3]
	v_mad_u64_u32 v[30:31], s[40:41], v30, s46, v[2:3]
	v_mad_u64_u32 v[34:35], s[40:41], v34, s46, v[2:3]
	v_mad_u64_u32 v[36:37], s[40:41], v36, s46, v[2:3]
	v_mad_u64_u32 v[66:67], s[40:41], v66, s46, v[2:3]
	v_mad_u64_u32 v[68:69], s[40:41], v68, s46, v[2:3]
	v_mad_u64_u32 v[70:71], s[40:41], v70, s46, v[2:3]
	v_mad_u64_u32 v[72:73], s[40:41], v72, s46, v[2:3]
	v_mad_u64_u32 v[74:75], s[40:41], v74, s46, v[2:3]
	v_mad_u64_u32 v[76:77], s[40:41], v76, s46, v[2:3]
	s_waitcnt vmcnt(15)
	ds_write_b32 v14, v11
	s_waitcnt vmcnt(14)
	ds_write_b32 v18, v78
	s_waitcnt vmcnt(13)
	ds_write_b32 v20, v79
	s_waitcnt vmcnt(12)
	ds_write_b32 v22, v80
	s_waitcnt vmcnt(11)
	ds_write_b32 v24, v81
	s_waitcnt vmcnt(10)
	ds_write_b32 v26, v82
	s_waitcnt vmcnt(9)
	ds_write_b32 v28, v83
	s_waitcnt vmcnt(8)
	ds_write_b32 v30, v84
	s_waitcnt vmcnt(7)
	ds_write_b32 v34, v85
	s_waitcnt vmcnt(6)
	ds_write_b32 v36, v86
	s_waitcnt vmcnt(5)
	ds_write_b32 v66, v87
	s_waitcnt vmcnt(4)
	ds_write_b32 v68, v88
	s_waitcnt vmcnt(3)
	ds_write_b32 v70, v89
	s_waitcnt vmcnt(2)
	ds_write_b32 v72, v90
	s_waitcnt vmcnt(1)
	ds_write_b32 v74, v91
	s_waitcnt vmcnt(0)
	ds_write_b32 v76, v92
	s_cbranch_scc1 .LBB0_66
	s_waitcnt lgkmcnt(0)
	ds_read2_b32 v[14:15], v33 offset0:33 offset1:41
	ds_read2_b32 v[18:19], v33 offset1:8
	ds_read2_b32 v[20:21], v33 offset0:66 offset1:74
	ds_read2_b32 v[22:23], v33 offset0:99 offset1:107
	ds_read2_b32 v[24:25], v33 offset0:132 offset1:140
	ds_read2_b32 v[26:27], v33 offset0:165 offset1:173
	ds_read2_b32 v[28:29], v33 offset0:198 offset1:206
	ds_read2_b32 v[30:31], v33 offset0:231 offset1:239
	v_or_b32_e32 v36, v9, v17
	v_ashrrev_i32_e32 v11, 31, v10
	v_ashrrev_i32_e32 v37, 31, v36
	v_lshl_add_u64 v[34:35], v[10:11], 1, v[6:7]
	v_lshlrev_b64 v[36:37], 11, v[36:37]
	s_waitcnt lgkmcnt(6)
	v_cvt_pk_bf16_f32 v10, v18, v14
	s_waitcnt lgkmcnt(4)
	v_cvt_pk_bf16_f32 v11, v20, v22
	s_waitcnt lgkmcnt(2)
	v_cvt_pk_bf16_f32 v12, v24, v26
	s_waitcnt lgkmcnt(0)
	v_cvt_pk_bf16_f32 v13, v28, v30
	v_lshl_add_u64 v[36:37], v[34:35], 0, v[36:37]
	v_or_b32_e32 v14, v9, v38
	global_store_dwordx4 v[36:37], v[10:13], off nt
	s_nop 1
	v_cvt_pk_bf16_f32 v10, v19, v15
	v_ashrrev_i32_e32 v15, 31, v14
	v_cvt_pk_bf16_f32 v11, v21, v23
	v_cvt_pk_bf16_f32 v12, v25, v27
	v_cvt_pk_bf16_f32 v13, v29, v31
	v_lshlrev_b64 v[14:15], 11, v[14:15]
	ds_read2_b32 v[18:19], v33 offset0:49 offset1:57
	ds_read2_b32 v[20:21], v33 offset0:16 offset1:24
	ds_read2_b32 v[22:23], v33 offset0:82 offset1:90
	ds_read2_b32 v[24:25], v33 offset0:115 offset1:123
	ds_read2_b32 v[26:27], v33 offset0:148 offset1:156
	ds_read2_b32 v[28:29], v33 offset0:181 offset1:189
	ds_read2_b32 v[30:31], v33 offset0:214 offset1:222
	ds_read2_b32 v[36:37], v33 offset0:247 offset1:255
	v_lshl_add_u64 v[14:15], v[34:35], 0, v[14:15]
	global_store_dwordx4 v[14:15], v[10:13], off nt
	v_or_b32_e32 v14, v9, v39
	v_ashrrev_i32_e32 v15, 31, v14
	v_lshlrev_b64 v[14:15], 11, v[14:15]
	s_waitcnt lgkmcnt(6)
	v_cvt_pk_bf16_f32 v10, v20, v18
	s_waitcnt lgkmcnt(4)
	v_cvt_pk_bf16_f32 v11, v22, v24
	s_waitcnt lgkmcnt(2)
	v_cvt_pk_bf16_f32 v12, v26, v28
	s_waitcnt lgkmcnt(0)
	v_cvt_pk_bf16_f32 v13, v30, v36
	v_lshl_add_u64 v[14:15], v[34:35], 0, v[14:15]
	global_store_dwordx4 v[14:15], v[10:13], off nt
	v_or_b32_e32 v14, v9, v40
	v_ashrrev_i32_e32 v15, 31, v14
	v_lshlrev_b64 v[14:15], 11, v[14:15]
	v_cvt_pk_bf16_f32 v10, v21, v19
	v_cvt_pk_bf16_f32 v11, v23, v25
	v_cvt_pk_bf16_f32 v12, v27, v29
	v_cvt_pk_bf16_f32 v13, v31, v37
	v_lshl_add_u64 v[14:15], v[34:35], 0, v[14:15]
	global_store_dwordx4 v[14:15], v[10:13], off nt
	s_waitcnt lgkmcnt(0)
	s_branch .LBB0_19

; template <bool FINAL> __device__ __forceinline__ void ln_pass(const Params& P, const float* g, const float* b, int tid_in) {
;     ...
;         for (int o = 1; o < 64; o <<= 1) q += __shfl_xor(q, o);
;         const float rstd = 1.f / sqrtf(q * (1.f / D) + LN_EPS);
;         float* yo = nullptr;
;         if (FINAL) { if (m < NPT) { const int bb = m / LP, t = m % LP; if (t >= 16) yo = P.out + O_YP + ((size_t)bb * 2048 + (t - 16)) * D; } else yo = P.out + O_YS + (size_t)(m - NPT) * D; }
; #pragma unroll
;         for (int j = 0; j < 4; ++j) {
;             const f32x4 y = v[j] * rstd * gv[j] + bv[j];
;             if (FINAL) { if (yo) *(f32x4*)(yo + 256 * j + 4 * lane) = y; }
.LBB0_1826:
	s_waitcnt lgkmcnt(0)
	v_add_f32_e32 v33, v33, v35
	v_fmamk_f32 v33, v33, 0x3a800000, v69
	v_mul_f32_e32 v35, 0x4f800000, v33
	v_cmp_gt_f32_e32 vcc, s14, v33
	v_mov_b32_e32 v78, v44
	v_mov_b32_e32 v82, v40
	v_cndmask_b32_e32 v33, v33, v35, vcc
	v_sqrt_f32_e32 v35, v33
	v_mov_b32_e32 v79, v72
	v_mov_b32_e32 v83, v70
	v_add_u32_e32 v44, -1, v35
	v_fma_f32 v62, -v44, v35, v33
	v_cmp_ge_f32_e64 s[2:3], 0, v62
	v_add_u32_e32 v62, 1, v35
	s_nop 0
	v_cndmask_b32_e64 v44, v35, v44, s[2:3]
	v_fma_f32 v35, -v62, v35, v33
	v_cmp_lt_f32_e64 s[2:3], 0, v35
	s_nop 1
	v_cndmask_b32_e64 v35, v44, v62, s[2:3]
	v_mul_f32_e32 v44, 0x37800000, v35
	v_cndmask_b32_e32 v35, v35, v44, vcc
	v_cmp_class_f32_e32 vcc, v33, v80
	s_nop 1
	v_cndmask_b32_e32 v35, v35, v33, vcc
	v_div_scale_f32 v44, s[2:3], v35, v35, 1.0
	v_rcp_f32_e32 v62, v44
	v_mov_b32_e32 v33, v74
	v_fma_f32 v40, -v44, v62, 1.0
	v_fmac_f32_e32 v62, v40, v62
	v_div_scale_f32 v40, vcc, 1.0, v35, 1.0
	v_mul_f32_e32 v65, v40, v62
	v_fma_f32 v68, -v44, v65, v40
	v_fmac_f32_e32 v65, v68, v62
	v_fma_f32 v40, -v44, v65, v40
	v_div_fmas_f32 v40, v40, v62, v65
	v_div_fixup_f32 v62, v40, v35, 1.0
	v_mov_b32_e32 v44, v73
	v_mov_b32_e32 v65, v63
	v_pk_mul_f32 v[78:79], v[78:79], v[62:63] op_sel_hi:[1,0]
	v_pk_mul_f32 v[44:45], v[44:45], v[62:63] op_sel_hi:[1,0]
	v_mov_b32_e32 v40, v71
	v_mov_b32_e32 v35, v42
	v_lshl_add_u64 v[76:77], v[76:77], 0, v[64:65]
	s_nop 0
	v_pk_fma_f32 v[74:75], v[2:3], v[44:45], v[30:31]
	v_pk_fma_f32 v[72:73], v[0:1], v[78:79], v[28:29]
	v_pk_mul_f32 v[44:45], v[82:83], v[62:63] op_sel_hi:[1,0]
	v_pk_mul_f32 v[40:41], v[40:41], v[62:63] op_sel_hi:[1,0]
	v_pk_mul_f32 v[36:37], v[36:37], v[62:63] op_sel_hi:[1,0]
	v_pk_mul_f32 v[38:39], v[38:39], v[62:63] op_sel_hi:[1,0]
	v_pk_mul_f32 v[32:33], v[32:33], v[62:63] op_sel_hi:[1,0]
	v_pk_mul_f32 v[34:35], v[34:35], v[62:63] op_sel_hi:[1,0]
	global_store_dwordx4 v[76:77], v[72:75], off nt
	v_pk_fma_f32 v[70:71], v[4:5], v[44:45], v[12:13]
	v_pk_fma_f32 v[38:39], v[10:11], v[38:39], v[18:19]
	v_pk_fma_f32 v[72:73], v[6:7], v[40:41], v[14:15]
	v_pk_fma_f32 v[36:37], v[8:9], v[36:37], v[16:17]
	v_pk_fma_f32 v[34:35], v[22:23], v[34:35], v[26:27]
	v_pk_fma_f32 v[32:33], v[20:21], v[32:33], v[24:25]
	global_store_dwordx4 v[76:77], v[70:73], off offset:1024 nt
	global_store_dwordx4 v[76:77], v[36:39], off offset:2048 nt
	global_store_dwordx4 v[76:77], v[32:35], off offset:3072 nt
